# SGPR-base LDS-DMA + removed s_nop lines that are not M0 wait states in the K-loops
# speedup vs baseline: 1.0075x; 1.0004x over previous
; #define PG8_STAGE(bufoff, gbase, voff) do { _Pragma("unroll") for (int _i = 0; _i < 2; ++_i) \
;         __builtin_amdgcn_global_load_lds((const unsigned*)((const char*)(gbase) + (voff)[_i]), (PG8_LAS unsigned*)(lds + (bufoff) + ldsw + _i * 8192), 16, 0, 0); } while (0)
; #define PG8_LDA(dst, b, h) do { _Pragma("unroll") for (int m = 0; m < 4; ++m) _Pragma("unroll") for (int k = 0; k < 2; ++k) dst[m][k] = *(const PG8_LAS bf16x8*)(lds + PG8_SA(b, h) + aoff + m * 2048 + k * 1024); } while (0)
; #define PG8_LDB(dst, b, h) do { _Pragma("unroll") for (int n = 0; n < 2; ++n) _Pragma("unroll") for (int k = 0; k < 2; ++k) dst[n][k] = *(const PG8_LAS bf16x8*)(lds + PG8_SB(b, h) + boff + n * 2048 + k * 1024); } while (0)
; #define PG8_MMA(ai, bj, At, Bt) do { __builtin_amdgcn_s_setprio(1); _Pragma("unroll") for (int m = 0; m < 4; ++m) _Pragma("unroll") for (int n = 0; n < 2; ++n) _Pragma("unroll") for (int k = 0; k < 2; ++k) \
;         acc[ai][bj][m][n] = __builtin_amdgcn_mfma_f32_16x16x32_bf16(Bt[n][k], At[m][k], acc[ai][bj][m][n], 0, 0, 0); __builtin_amdgcn_s_setprio(0); } while (0)
; #define PG8_WAIT_V(n) asm volatile("s_waitcnt vmcnt(" #n ")" ::: "memory")
; #define PG8_WAIT_L(n) asm volatile("s_waitcnt lgkmcnt(" #n ")" ::: "memory")
; #define PG8_BAR __builtin_amdgcn_s_barrier()
; template <class Epi, class Sched, bool ALIGN_EPI = false, bool SP2 = false>
; __device__ __forceinline__ void gemm_phase(PG8_LAS unsigned char* lds, const Gemm g, const Sched& S, const Epi& E, int wave_s) {
;     ...
;             const char* a1 = cA + (size_t)(t + 1) * kstep;
;             const char* a2 = last ? nA : cA + (size_t)(t + 2) * kstep; const char* b2 = last ? nB : cB + (size_t)(t + 2) * kstep;
;             const char* a3 = a2 + kstep; const char* b3 = b2 + kstep;
;             if (last && has_next) S.a_ready(nxt);
;             if constexpr (SP2) {
;             PG8_LDB(B0, 0, 0); PG8_LDB(B1, 0, 1); PG8_SCHED; PG8_LDA(At, 0, 0); PG8_STAGE(PG8_SA(1, 1), a1 + hstep, voffA);
;             PG8_WAIT_V(8); PG8_WAIT_L(0); PG8_BAR; PG8_MMA(0, 0, At, B0); PG8_MMA(0, 1, At, B1); PG8_BAR; PG8_SCHED;
;             PG8_LDA(At, 0, 1); PG8_STAGE(PG8_SB(0, 0), b2, voffB); PG8_STAGE(PG8_SB(0, 1), b2 + hstep, voffB); PG8_STAGE(PG8_SA(0, 0), a2, voffA);
;             PG8_WAIT_V(8); PG8_WAIT_L(0); PG8_BAR; PG8_MMA(1, 0, At, B0); PG8_MMA(1, 1, At, B1); PG8_BAR; PG8_SCHED;
.LBB0_41:
	ds_read_b128 v[144:147], v158 offset:3072
	ds_read_b128 v[148:151], v158 offset:2048
	ds_read_b128 v[152:155], v158 offset:1024
	ds_read_b128 v[160:163], v158
	ds_read_b128 v[164:167], v157 offset:3072
	ds_read_b128 v[168:171], v157 offset:2048
	ds_read_b128 v[172:175], v157 offset:1024
	ds_read_b128 v[176:179], v157
	s_add_u32 s48, s46, 0xfff00080
	s_addc_u32 s49, s47, -1
	s_cmp_eq_u32 s86, 60
	s_cselect_b32 s51, s31, s49
	s_cselect_b32 s50, s72, s48
	s_cselect_b32 s49, s35, s85
	s_cselect_b32 s48, s73, s84
	s_mov_b32 m0, s74
	s_nop 0
	ds_read_b128 v[180:183], v159
	ds_read_b128 v[184:187], v159 offset:1024
	ds_read_b128 v[188:191], v159 offset:2048
	ds_read_b128 v[192:195], v159 offset:3072
	ds_read_b128 v[196:199], v159 offset:4096
	ds_read_b128 v[200:203], v159 offset:5120
	ds_read_b128 v[204:207], v159 offset:6144
	ds_read_b128 v[208:211], v159 offset:7168
	global_load_lds_dwordx4 v138, s[46:47]
	s_mov_b32 m0, s75
	s_nop 0
	global_load_lds_dwordx4 v140, s[46:47]
	s_waitcnt vmcnt(8)
	s_waitcnt lgkmcnt(0)
	s_barrier
	v_mfma_f32_16x16x32_bf16 v[124:127], v[176:179], v[180:183], v[124:127]
	v_mfma_f32_16x16x32_bf16 v[124:127], v[172:175], v[184:187], v[124:127]
	v_mfma_f32_16x16x32_bf16 v[120:123], v[164:167], v[184:187], v[120:123]
	v_mfma_f32_16x16x32_bf16 v[120:123], v[168:171], v[180:183], v[120:123]
	v_mfma_f32_16x16x32_bf16 v[104:107], v[168:171], v[188:191], v[104:107]
	v_mfma_f32_16x16x32_bf16 v[104:107], v[164:167], v[192:195], v[104:107]
	v_mfma_f32_16x16x32_bf16 v[108:111], v[172:175], v[192:195], v[108:111]
	v_mfma_f32_16x16x32_bf16 v[108:111], v[176:179], v[188:191], v[108:111]
	v_mfma_f32_16x16x32_bf16 v[92:95], v[176:179], v[196:199], v[92:95]
	v_mfma_f32_16x16x32_bf16 v[92:95], v[172:175], v[200:203], v[92:95]
	v_mfma_f32_16x16x32_bf16 v[88:91], v[164:167], v[200:203], v[88:91]
	v_mfma_f32_16x16x32_bf16 v[88:91], v[168:171], v[196:199], v[88:91]
	v_mfma_f32_16x16x32_bf16 v[56:59], v[168:171], v[204:207], v[56:59]
	v_mfma_f32_16x16x32_bf16 v[56:59], v[164:167], v[208:211], v[56:59]
	v_mfma_f32_16x16x32_bf16 v[64:67], v[172:175], v[208:211], v[64:67]
	v_mfma_f32_16x16x32_bf16 v[64:67], v[176:179], v[204:207], v[64:67]
	v_mfma_f32_16x16x32_bf16 v[116:119], v[160:163], v[180:183], v[116:119]
	v_mfma_f32_16x16x32_bf16 v[116:119], v[152:155], v[184:187], v[116:119]
	v_mfma_f32_16x16x32_bf16 v[112:115], v[144:147], v[184:187], v[112:115]
	v_mfma_f32_16x16x32_bf16 v[112:115], v[148:151], v[180:183], v[112:115]
	v_mfma_f32_16x16x32_bf16 v[96:99], v[148:151], v[188:191], v[96:99]
	v_mfma_f32_16x16x32_bf16 v[96:99], v[144:147], v[192:195], v[96:99]
	v_mfma_f32_16x16x32_bf16 v[100:103], v[152:155], v[192:195], v[100:103]
	v_mfma_f32_16x16x32_bf16 v[100:103], v[160:163], v[188:191], v[100:103]
	v_mfma_f32_16x16x32_bf16 v[84:87], v[160:163], v[196:199], v[84:87]
	v_mfma_f32_16x16x32_bf16 v[84:87], v[152:155], v[200:203], v[84:87]
	v_mfma_f32_16x16x32_bf16 v[80:83], v[144:147], v[200:203], v[80:83]
	v_mfma_f32_16x16x32_bf16 v[80:83], v[148:151], v[196:199], v[80:83]
	v_mfma_f32_16x16x32_bf16 v[48:51], v[148:151], v[204:207], v[48:51]
	v_mfma_f32_16x16x32_bf16 v[48:51], v[144:147], v[208:211], v[48:51]
	v_mfma_f32_16x16x32_bf16 v[52:55], v[152:155], v[208:211], v[52:55]
	v_mfma_f32_16x16x32_bf16 v[52:55], v[160:163], v[204:207], v[52:55]
	s_barrier
	s_mov_b32 m0, s76
	s_nop 0
	s_add_u32 s88, s48, 0x100000
	ds_read_b128 v[180:183], v159 offset:16384
	ds_read_b128 v[184:187], v159 offset:17408
	ds_read_b128 v[188:191], v159 offset:18432
	ds_read_b128 v[192:195], v159 offset:19456
	ds_read_b128 v[196:199], v159 offset:20480
	ds_read_b128 v[200:203], v159 offset:21504
	ds_read_b128 v[204:207], v159 offset:22528
	ds_read_b128 v[208:211], v159 offset:23552
	global_load_lds_dwordx4 v132, s[48:49]
	s_mov_b32 m0, s77
	s_addc_u32 s89, s49, 0
	global_load_lds_dwordx4 v128, s[48:49]
	s_mov_b32 m0, s78
	s_nop 0
	global_load_lds_dwordx4 v132, s[88:89]
	s_mov_b32 m0, s79
	s_nop 0
	global_load_lds_dwordx4 v128, s[88:89]
	s_mov_b32 m0, s43
	s_nop 0
	global_load_lds_dwordx4 v134, s[50:51]
	s_mov_b32 m0, s57
	s_nop 0
	global_load_lds_dwordx4 v130, s[50:51]
	s_waitcnt vmcnt(8)
	s_waitcnt lgkmcnt(0)
	s_barrier
	v_mfma_f32_16x16x32_bf16 v[76:79], v[176:179], v[180:183], v[76:79]
	v_mfma_f32_16x16x32_bf16 v[76:79], v[172:175], v[184:187], v[76:79]
	v_mfma_f32_16x16x32_bf16 v[72:75], v[164:167], v[184:187], v[72:75]
	v_mfma_f32_16x16x32_bf16 v[72:75], v[168:171], v[180:183], v[72:75]
	v_mfma_f32_16x16x32_bf16 v[40:43], v[168:171], v[188:191], v[40:43]
	v_mfma_f32_16x16x32_bf16 v[40:43], v[164:167], v[192:195], v[40:43]
	v_mfma_f32_16x16x32_bf16 v[44:47], v[172:175], v[192:195], v[44:47]
	v_mfma_f32_16x16x32_bf16 v[44:47], v[176:179], v[188:191], v[44:47]
	v_mfma_f32_16x16x32_bf16 v[28:31], v[176:179], v[196:199], v[28:31]
	v_mfma_f32_16x16x32_bf16 v[28:31], v[172:175], v[200:203], v[28:31]
	v_mfma_f32_16x16x32_bf16 v[24:27], v[164:167], v[200:203], v[24:27]
	v_mfma_f32_16x16x32_bf16 v[24:27], v[168:171], v[196:199], v[24:27]
	v_mfma_f32_16x16x32_bf16 v[8:11], v[168:171], v[204:207], v[8:11]
	v_mfma_f32_16x16x32_bf16 v[8:11], v[164:167], v[208:211], v[8:11]
	v_mfma_f32_16x16x32_bf16 v[12:15], v[172:175], v[208:211], v[12:15]
	v_mfma_f32_16x16x32_bf16 v[12:15], v[176:179], v[204:207], v[12:15]
	v_mfma_f32_16x16x32_bf16 v[68:71], v[160:163], v[180:183], v[68:71]
	v_mfma_f32_16x16x32_bf16 v[68:71], v[152:155], v[184:187], v[68:71]
	v_mfma_f32_16x16x32_bf16 v[60:63], v[144:147], v[184:187], v[60:63]
	v_mfma_f32_16x16x32_bf16 v[60:63], v[148:151], v[180:183], v[60:63]
	v_mfma_f32_16x16x32_bf16 v[32:35], v[148:151], v[188:191], v[32:35]
	v_mfma_f32_16x16x32_bf16 v[32:35], v[144:147], v[192:195], v[32:35]
	v_mfma_f32_16x16x32_bf16 v[36:39], v[152:155], v[192:195], v[36:39]
	v_mfma_f32_16x16x32_bf16 v[36:39], v[160:163], v[188:191], v[36:39]
	v_mfma_f32_16x16x32_bf16 v[20:23], v[160:163], v[196:199], v[20:23]
	v_mfma_f32_16x16x32_bf16 v[20:23], v[152:155], v[200:203], v[20:23]
	v_mfma_f32_16x16x32_bf16 v[16:19], v[144:147], v[200:203], v[16:19]
	v_mfma_f32_16x16x32_bf16 v[16:19], v[148:151], v[196:199], v[16:19]
	v_mfma_f32_16x16x32_bf16 v[0:3], v[148:151], v[204:207], v[0:3]
	v_mfma_f32_16x16x32_bf16 v[0:3], v[144:147], v[208:211], v[0:3]
	v_mfma_f32_16x16x32_bf16 v[4:7], v[152:155], v[208:211], v[4:7]
	v_mfma_f32_16x16x32_bf16 v[4:7], v[160:163], v[204:207], v[4:7]
	s_barrier
; #define PG8_STAGE(bufoff, gbase, voff) do { _Pragma("unroll") for (int _i = 0; _i < 2; ++_i) \
;         __builtin_amdgcn_global_load_lds((const unsigned*)((const char*)(gbase) + (voff)[_i]), (PG8_LAS unsigned*)(lds + (bufoff) + ldsw + _i * 8192), 16, 0, 0); } while (0)
; #define PG8_LDA(dst, b, h) do { _Pragma("unroll") for (int m = 0; m < 4; ++m) _Pragma("unroll") for (int k = 0; k < 2; ++k) dst[m][k] = *(const PG8_LAS bf16x8*)(lds + PG8_SA(b, h) + aoff + m * 2048 + k * 1024); } while (0)
; #define PG8_LDB(dst, b, h) do { _Pragma("unroll") for (int n = 0; n < 2; ++n) _Pragma("unroll") for (int k = 0; k < 2; ++k) dst[n][k] = *(const PG8_LAS bf16x8*)(lds + PG8_SB(b, h) + boff + n * 2048 + k * 1024); } while (0)
; #define PG8_MMA(ai, bj, At, Bt) do { __builtin_amdgcn_s_setprio(1); _Pragma("unroll") for (int m = 0; m < 4; ++m) _Pragma("unroll") for (int n = 0; n < 2; ++n) _Pragma("unroll") for (int k = 0; k < 2; ++k) \
;         acc[ai][bj][m][n] = __builtin_amdgcn_mfma_f32_16x16x32_bf16(Bt[n][k], At[m][k], acc[ai][bj][m][n], 0, 0, 0); __builtin_amdgcn_s_setprio(0); } while (0)
; #define PG8_WAIT_V(n) asm volatile("s_waitcnt vmcnt(" #n ")" ::: "memory")
; #define PG8_WAIT_L(n) asm volatile("s_waitcnt lgkmcnt(" #n ")" ::: "memory")
; #define PG8_BAR __builtin_amdgcn_s_barrier()
; #define PG8_SCHED __builtin_amdgcn_sched_barrier(0)
; template <class Epi, class Sched, bool ALIGN_EPI = false, bool SP2 = false>
; __device__ __forceinline__ void gemm_phase(PG8_LAS unsigned char* lds, const Gemm g, const Sched& S, const Epi& E, int wave_s) {
;     ...
;             PG8_LDB(B0, 1, 0); PG8_LDB(B1, 1, 1); PG8_SCHED; PG8_LDA(At, 1, 0); PG8_STAGE(PG8_SA(0, 1), a2 + hstep, voffA);
;             PG8_WAIT_V(8); PG8_WAIT_L(0); PG8_BAR; PG8_MMA(0, 0, At, B0); PG8_MMA(0, 1, At, B1); PG8_BAR; PG8_SCHED;
;             PG8_LDA(At, 1, 1); PG8_STAGE(PG8_SB(1, 0), b3, voffB); PG8_STAGE(PG8_SB(1, 1), b3 + hstep, voffB); PG8_STAGE(PG8_SA(1, 0), a3, voffA);
;             PG8_WAIT_V(8); PG8_WAIT_L(0); PG8_BAR; PG8_MMA(1, 0, At, B0); PG8_MMA(1, 1, At, B1); PG8_BAR; PG8_SCHED;
	ds_read_b128 v[144:147], v142
	ds_read_b128 v[148:151], v142 offset:1024
	ds_read_b128 v[152:155], v142 offset:2048
	ds_read_b128 v[160:163], v142 offset:3072
	ds_read_b128 v[164:167], v143
	ds_read_b128 v[168:171], v143 offset:1024
	ds_read_b128 v[172:175], v143 offset:2048
	ds_read_b128 v[176:179], v143 offset:3072
	s_add_u32 s50, s50, 0x100000
	s_addc_u32 s51, s51, 0
	s_mov_b32 m0, s58
	s_nop 0
	ds_read_b128 v[180:183], v159 offset:32768
	ds_read_b128 v[184:187], v159 offset:33792
	ds_read_b128 v[188:191], v159 offset:34816
	ds_read_b128 v[192:195], v159 offset:35840
	ds_read_b128 v[196:199], v159 offset:36864
	ds_read_b128 v[200:203], v159 offset:37888
	ds_read_b128 v[204:207], v159 offset:38912
	ds_read_b128 v[208:211], v159 offset:39936
	global_load_lds_dwordx4 v134, s[50:51]
	s_mov_b32 m0, s59
	s_nop 0
	global_load_lds_dwordx4 v130, s[50:51]
	s_waitcnt vmcnt(8)
	s_waitcnt lgkmcnt(0)
	s_barrier
	v_mfma_f32_16x16x32_bf16 v[124:127], v[144:147], v[180:183], v[124:127]
	v_mfma_f32_16x16x32_bf16 v[124:127], v[148:151], v[184:187], v[124:127]
	v_mfma_f32_16x16x32_bf16 v[120:123], v[160:163], v[184:187], v[120:123]
	v_mfma_f32_16x16x32_bf16 v[120:123], v[152:155], v[180:183], v[120:123]
	v_mfma_f32_16x16x32_bf16 v[104:107], v[152:155], v[188:191], v[104:107]
	v_mfma_f32_16x16x32_bf16 v[104:107], v[160:163], v[192:195], v[104:107]
	v_mfma_f32_16x16x32_bf16 v[108:111], v[148:151], v[192:195], v[108:111]
	v_mfma_f32_16x16x32_bf16 v[108:111], v[144:147], v[188:191], v[108:111]
	v_mfma_f32_16x16x32_bf16 v[92:95], v[144:147], v[196:199], v[92:95]
	v_mfma_f32_16x16x32_bf16 v[92:95], v[148:151], v[200:203], v[92:95]
	v_mfma_f32_16x16x32_bf16 v[88:91], v[160:163], v[200:203], v[88:91]
	v_mfma_f32_16x16x32_bf16 v[88:91], v[152:155], v[196:199], v[88:91]
	v_mfma_f32_16x16x32_bf16 v[56:59], v[152:155], v[204:207], v[56:59]
	v_mfma_f32_16x16x32_bf16 v[56:59], v[160:163], v[208:211], v[56:59]
	v_mfma_f32_16x16x32_bf16 v[64:67], v[148:151], v[208:211], v[64:67]
	v_mfma_f32_16x16x32_bf16 v[64:67], v[144:147], v[204:207], v[64:67]
	v_mfma_f32_16x16x32_bf16 v[116:119], v[164:167], v[180:183], v[116:119]
	v_mfma_f32_16x16x32_bf16 v[116:119], v[168:171], v[184:187], v[116:119]
	v_mfma_f32_16x16x32_bf16 v[112:115], v[176:179], v[184:187], v[112:115]
	v_mfma_f32_16x16x32_bf16 v[112:115], v[172:175], v[180:183], v[112:115]
	v_mfma_f32_16x16x32_bf16 v[96:99], v[172:175], v[188:191], v[96:99]
	v_mfma_f32_16x16x32_bf16 v[96:99], v[176:179], v[192:195], v[96:99]
	v_mfma_f32_16x16x32_bf16 v[100:103], v[168:171], v[192:195], v[100:103]
	v_mfma_f32_16x16x32_bf16 v[100:103], v[164:167], v[188:191], v[100:103]
	v_mfma_f32_16x16x32_bf16 v[84:87], v[164:167], v[196:199], v[84:87]
	v_mfma_f32_16x16x32_bf16 v[84:87], v[168:171], v[200:203], v[84:87]
	v_mfma_f32_16x16x32_bf16 v[80:83], v[176:179], v[200:203], v[80:83]
	v_mfma_f32_16x16x32_bf16 v[80:83], v[172:175], v[196:199], v[80:83]
	v_mfma_f32_16x16x32_bf16 v[48:51], v[172:175], v[204:207], v[48:51]
	v_mfma_f32_16x16x32_bf16 v[48:51], v[176:179], v[208:211], v[48:51]
	v_mfma_f32_16x16x32_bf16 v[52:55], v[168:171], v[208:211], v[52:55]
	v_mfma_f32_16x16x32_bf16 v[52:55], v[164:167], v[204:207], v[52:55]
	s_barrier
	s_mov_b32 m0, s80
	s_nop 0
	s_add_u32 s94, s48, 0x80
	s_addc_u32 s95, s49, 0
	s_add_u32 s48, s48, 0x100080
	ds_read_b128 v[180:183], v159 offset:49152
	ds_read_b128 v[184:187], v159 offset:50176
	ds_read_b128 v[188:191], v159 offset:51200
	ds_read_b128 v[192:195], v159 offset:52224
	ds_read_b128 v[196:199], v159 offset:53248
	ds_read_b128 v[200:203], v159 offset:54272
	ds_read_b128 v[204:207], v159 offset:55296
	ds_read_b128 v[208:211], v159 offset:56320
	global_load_lds_dwordx4 v132, s[94:95]
	s_mov_b32 m0, s81
	s_addc_u32 s49, s49, 0
	global_load_lds_dwordx4 v128, s[94:95]
	s_mov_b32 m0, s82
	s_nop 0
	global_load_lds_dwordx4 v132, s[48:49]
	s_mov_b32 m0, s83
	s_nop 0
	global_load_lds_dwordx4 v128, s[48:49]
	s_mov_b32 m0, s64
	s_nop 0
	s_add_u32 s96, s50, 0xfff00080
	s_addc_u32 s97, s51, -1
	global_load_lds_dwordx4 v134, s[96:97]
	s_mov_b32 m0, s65
	s_nop 0
	global_load_lds_dwordx4 v130, s[96:97]
	s_waitcnt vmcnt(8)
	s_waitcnt lgkmcnt(0)
	s_barrier
	v_mfma_f32_16x16x32_bf16 v[76:79], v[144:147], v[180:183], v[76:79]
	v_mfma_f32_16x16x32_bf16 v[76:79], v[148:151], v[184:187], v[76:79]
	v_mfma_f32_16x16x32_bf16 v[72:75], v[160:163], v[184:187], v[72:75]
	v_mfma_f32_16x16x32_bf16 v[72:75], v[152:155], v[180:183], v[72:75]
	v_mfma_f32_16x16x32_bf16 v[40:43], v[152:155], v[188:191], v[40:43]
	v_mfma_f32_16x16x32_bf16 v[40:43], v[160:163], v[192:195], v[40:43]
	v_mfma_f32_16x16x32_bf16 v[44:47], v[148:151], v[192:195], v[44:47]
	v_mfma_f32_16x16x32_bf16 v[44:47], v[144:147], v[188:191], v[44:47]
	v_mfma_f32_16x16x32_bf16 v[28:31], v[144:147], v[196:199], v[28:31]
	v_mfma_f32_16x16x32_bf16 v[28:31], v[148:151], v[200:203], v[28:31]
	v_mfma_f32_16x16x32_bf16 v[24:27], v[160:163], v[200:203], v[24:27]
	v_mfma_f32_16x16x32_bf16 v[24:27], v[152:155], v[196:199], v[24:27]
	v_mfma_f32_16x16x32_bf16 v[8:11], v[152:155], v[204:207], v[8:11]
	v_mfma_f32_16x16x32_bf16 v[8:11], v[160:163], v[208:211], v[8:11]
	v_mfma_f32_16x16x32_bf16 v[12:15], v[148:151], v[208:211], v[12:15]
	v_mfma_f32_16x16x32_bf16 v[12:15], v[144:147], v[204:207], v[12:15]
	v_mfma_f32_16x16x32_bf16 v[68:71], v[164:167], v[180:183], v[68:71]
	v_mfma_f32_16x16x32_bf16 v[68:71], v[168:171], v[184:187], v[68:71]
	v_mfma_f32_16x16x32_bf16 v[60:63], v[176:179], v[184:187], v[60:63]
	v_mfma_f32_16x16x32_bf16 v[60:63], v[172:175], v[180:183], v[60:63]
	v_mfma_f32_16x16x32_bf16 v[32:35], v[172:175], v[188:191], v[32:35]
	v_mfma_f32_16x16x32_bf16 v[32:35], v[176:179], v[192:195], v[32:35]
	v_mfma_f32_16x16x32_bf16 v[36:39], v[168:171], v[192:195], v[36:39]
	v_mfma_f32_16x16x32_bf16 v[36:39], v[164:167], v[188:191], v[36:39]
	v_mfma_f32_16x16x32_bf16 v[20:23], v[164:167], v[196:199], v[20:23]
	v_mfma_f32_16x16x32_bf16 v[20:23], v[168:171], v[200:203], v[20:23]
	v_mfma_f32_16x16x32_bf16 v[16:19], v[176:179], v[200:203], v[16:19]
	v_mfma_f32_16x16x32_bf16 v[16:19], v[172:175], v[196:199], v[16:19]
	v_mfma_f32_16x16x32_bf16 v[0:3], v[172:175], v[204:207], v[0:3]
	v_mfma_f32_16x16x32_bf16 v[0:3], v[176:179], v[208:211], v[0:3]
	v_mfma_f32_16x16x32_bf16 v[4:7], v[168:171], v[208:211], v[4:7]
	v_mfma_f32_16x16x32_bf16 v[4:7], v[164:167], v[204:207], v[4:7]
	s_barrier
	s_add_i32 s86, s86, 2
	s_add_u32 s46, s46, 0x100
	s_addc_u32 s47, s47, 0
	s_add_u32 s84, s84, 0x100
	s_addc_u32 s85, s85, 0
	s_cmp_gt_u32 s86, 61
	s_cbranch_scc0 .LBB0_41
	s_and_b64 vcc, exec, s[14:15]
	s_cbranch_vccz .LBB0_44
	s_barrier

; #define PG8_STAGE(bufoff, gbase, voff) do { _Pragma("unroll") for (int _i = 0; _i < 2; ++_i) \
;         __builtin_amdgcn_global_load_lds((const unsigned*)((const char*)(gbase) + (voff)[_i]), (PG8_LAS unsigned*)(lds + (bufoff) + ldsw + _i * 8192), 16, 0, 0); } while (0)
; #define PG8_LDA(dst, b, h) do { _Pragma("unroll") for (int m = 0; m < 4; ++m) _Pragma("unroll") for (int k = 0; k < 2; ++k) dst[m][k] = *(const PG8_LAS bf16x8*)(lds + PG8_SA(b, h) + aoff + m * 2048 + k * 1024); } while (0)
; #define PG8_LDB(dst, b, h) do { _Pragma("unroll") for (int n = 0; n < 2; ++n) _Pragma("unroll") for (int k = 0; k < 2; ++k) dst[n][k] = *(const PG8_LAS bf16x8*)(lds + PG8_SB(b, h) + boff + n * 2048 + k * 1024); } while (0)
; #define PG8_MMA(ai, bj, At, Bt) do { __builtin_amdgcn_s_setprio(1); _Pragma("unroll") for (int m = 0; m < 4; ++m) _Pragma("unroll") for (int n = 0; n < 2; ++n) _Pragma("unroll") for (int k = 0; k < 2; ++k) \
;         acc[ai][bj][m][n] = __builtin_amdgcn_mfma_f32_16x16x32_bf16(Bt[n][k], At[m][k], acc[ai][bj][m][n], 0, 0, 0); __builtin_amdgcn_s_setprio(0); } while (0)
; #define PG8_WAIT_V(n) asm volatile("s_waitcnt vmcnt(" #n ")" ::: "memory")
; #define PG8_WAIT_L(n) asm volatile("s_waitcnt lgkmcnt(" #n ")" ::: "memory")
; #define PG8_BAR __builtin_amdgcn_s_barrier()
; #define PG8_SCHED __builtin_amdgcn_sched_barrier(0)
; template <class Epi, class Sched, bool ALIGN_EPI = false, bool SP2 = false>
; __device__ __forceinline__ void gemm_phase(PG8_LAS unsigned char* lds, const Gemm g, const Sched& S, const Epi& E, int wave_s) {
;     ...
;             PG8_LDB(B0, 0, 0); PG8_LDB(B1, 0, 1); PG8_SCHED; PG8_LDA(At, 0, 0); PG8_STAGE(PG8_SA(1, 1), a1 + hstep, voffA);
;             PG8_WAIT_V(8); PG8_WAIT_L(0); PG8_BAR; PG8_MMA(0, 0, At, B0); PG8_MMA(0, 1, At, B1); PG8_BAR; PG8_SCHED;
;             PG8_LDA(At, 0, 1); PG8_STAGE(PG8_SB(0, 0), b2, voffB); PG8_STAGE(PG8_SB(0, 1), b2 + hstep, voffB); PG8_STAGE(PG8_SA(0, 0), a2, voffA);
;             PG8_WAIT_V(8); PG8_WAIT_L(0); PG8_BAR; PG8_MMA(1, 0, At, B0); PG8_MMA(1, 1, At, B1); PG8_BAR; PG8_SCHED;
.LBB0_1200:
	ds_read_b128 v[128:131], v211
	ds_read_b128 v[132:135], v211 offset:1024
	ds_read_b128 v[136:139], v211 offset:2048
	ds_read_b128 v[140:143], v211 offset:3072
	ds_read_b128 v[144:147], v212
	ds_read_b128 v[148:151], v212 offset:1024
	ds_read_b128 v[152:155], v212 offset:2048
	ds_read_b128 v[156:159], v212 offset:3072
	s_add_u32 s45, s50, 0xfff00080
	s_addc_u32 s52, s51, -1
	s_cmp_eq_u32 s85, s43
	s_cselect_b32 s55, s47, s52
	s_cselect_b32 s54, s46, s45
	s_cselect_b32 s53, s49, s41
	s_cselect_b32 s52, s48, s7
	s_add_i32 m0, s9, 0xc000
	ds_read_b128 v[160:163], v213
	ds_read_b128 v[164:167], v213 offset:1024
	ds_read_b128 v[168:171], v213 offset:2048
	ds_read_b128 v[172:175], v213 offset:3072
	ds_read_b128 v[176:179], v213 offset:4096
	ds_read_b128 v[180:183], v213 offset:5120
	ds_read_b128 v[196:199], v213 offset:6144
	ds_read_b128 v[200:203], v213 offset:7168
	global_load_lds_dwordx4 v192, s[50:51]
	s_add_i32 m0, s9, 0xe000
	s_nop 0
	global_load_lds_dwordx4 v194, s[50:51]
	s_waitcnt vmcnt(8)
	s_waitcnt lgkmcnt(0)
	s_barrier
	v_mfma_f32_16x16x32_bf16 v[124:127], v[128:131], v[160:163], v[124:127]
	v_mfma_f32_16x16x32_bf16 v[124:127], v[132:135], v[164:167], v[124:127]
	v_mfma_f32_16x16x32_bf16 v[120:123], v[140:143], v[164:167], v[120:123]
	v_mfma_f32_16x16x32_bf16 v[120:123], v[136:139], v[160:163], v[120:123]
	v_mfma_f32_16x16x32_bf16 v[104:107], v[136:139], v[168:171], v[104:107]
	v_mfma_f32_16x16x32_bf16 v[104:107], v[140:143], v[172:175], v[104:107]
	v_mfma_f32_16x16x32_bf16 v[108:111], v[132:135], v[172:175], v[108:111]
	v_mfma_f32_16x16x32_bf16 v[108:111], v[128:131], v[168:171], v[108:111]
	v_mfma_f32_16x16x32_bf16 v[92:95], v[128:131], v[176:179], v[92:95]
	v_mfma_f32_16x16x32_bf16 v[92:95], v[132:135], v[180:183], v[92:95]
	v_mfma_f32_16x16x32_bf16 v[88:91], v[140:143], v[180:183], v[88:91]
	v_mfma_f32_16x16x32_bf16 v[88:91], v[136:139], v[176:179], v[88:91]
	v_mfma_f32_16x16x32_bf16 v[72:75], v[136:139], v[196:199], v[72:75]
	v_mfma_f32_16x16x32_bf16 v[72:75], v[140:143], v[200:203], v[72:75]
	v_mfma_f32_16x16x32_bf16 v[76:79], v[132:135], v[200:203], v[76:79]
	v_mfma_f32_16x16x32_bf16 v[76:79], v[128:131], v[196:199], v[76:79]
	v_mfma_f32_16x16x32_bf16 v[116:119], v[144:147], v[160:163], v[116:119]
	v_mfma_f32_16x16x32_bf16 v[116:119], v[148:151], v[164:167], v[116:119]
	v_mfma_f32_16x16x32_bf16 v[112:115], v[156:159], v[164:167], v[112:115]
	v_mfma_f32_16x16x32_bf16 v[112:115], v[152:155], v[160:163], v[112:115]
	v_mfma_f32_16x16x32_bf16 v[96:99], v[152:155], v[168:171], v[96:99]
	v_mfma_f32_16x16x32_bf16 v[96:99], v[156:159], v[172:175], v[96:99]
	v_mfma_f32_16x16x32_bf16 v[100:103], v[148:151], v[172:175], v[100:103]
	v_mfma_f32_16x16x32_bf16 v[100:103], v[144:147], v[168:171], v[100:103]
	v_mfma_f32_16x16x32_bf16 v[84:87], v[144:147], v[176:179], v[84:87]
	v_mfma_f32_16x16x32_bf16 v[84:87], v[148:151], v[180:183], v[84:87]
	v_mfma_f32_16x16x32_bf16 v[80:83], v[156:159], v[180:183], v[80:83]
	v_mfma_f32_16x16x32_bf16 v[80:83], v[152:155], v[176:179], v[80:83]
	v_mfma_f32_16x16x32_bf16 v[64:67], v[152:155], v[196:199], v[64:67]
	v_mfma_f32_16x16x32_bf16 v[64:67], v[156:159], v[200:203], v[64:67]
	v_mfma_f32_16x16x32_bf16 v[68:71], v[148:151], v[200:203], v[68:71]
	v_mfma_f32_16x16x32_bf16 v[68:71], v[144:147], v[196:199], v[68:71]
	s_barrier
	s_add_i32 s45, s75, s60
	s_mov_b32 m0, s45
	ds_read_b128 v[160:163], v213 offset:16384
	ds_read_b128 v[164:167], v213 offset:17408
	ds_read_b128 v[168:171], v213 offset:18432
	ds_read_b128 v[172:175], v213 offset:19456
	ds_read_b128 v[176:179], v213 offset:20480
	ds_read_b128 v[180:183], v213 offset:21504
	ds_read_b128 v[196:199], v213 offset:22528
	ds_read_b128 v[200:203], v213 offset:23552
	global_load_lds_dwordx4 v186, s[52:53]
	s_add_i32 m0, s45, 0x2000
	s_add_u32 s86, s52, 0x100000
	s_addc_u32 s87, s53, 0
	s_add_i32 s45, s76, s60
	global_load_lds_dwordx4 v190, s[52:53]
	s_mov_b32 m0, s45
	s_nop 0
	global_load_lds_dwordx4 v186, s[86:87]
	s_add_i32 m0, s45, 0x2000
	s_nop 0
	global_load_lds_dwordx4 v190, s[86:87]
	s_mov_b32 m0, s9
	s_nop 0
	global_load_lds_dwordx4 v184, s[54:55]
	s_mov_b32 m0, s61
	s_nop 0
	global_load_lds_dwordx4 v188, s[54:55]
	s_waitcnt vmcnt(8)
	s_waitcnt lgkmcnt(0)
	s_barrier
	v_mfma_f32_16x16x32_bf16 v[60:63], v[128:131], v[160:163], v[60:63]
	v_mfma_f32_16x16x32_bf16 v[60:63], v[132:135], v[164:167], v[60:63]
	v_mfma_f32_16x16x32_bf16 v[56:59], v[140:143], v[164:167], v[56:59]
	v_mfma_f32_16x16x32_bf16 v[56:59], v[136:139], v[160:163], v[56:59]
	v_mfma_f32_16x16x32_bf16 v[40:43], v[136:139], v[168:171], v[40:43]
	v_mfma_f32_16x16x32_bf16 v[40:43], v[140:143], v[172:175], v[40:43]
	v_mfma_f32_16x16x32_bf16 v[44:47], v[132:135], v[172:175], v[44:47]
	v_mfma_f32_16x16x32_bf16 v[44:47], v[128:131], v[168:171], v[44:47]
	v_mfma_f32_16x16x32_bf16 v[28:31], v[128:131], v[176:179], v[28:31]
	v_mfma_f32_16x16x32_bf16 v[28:31], v[132:135], v[180:183], v[28:31]
	v_mfma_f32_16x16x32_bf16 v[24:27], v[140:143], v[180:183], v[24:27]
	v_mfma_f32_16x16x32_bf16 v[24:27], v[136:139], v[176:179], v[24:27]
	v_mfma_f32_16x16x32_bf16 v[8:11], v[136:139], v[196:199], v[8:11]
	v_mfma_f32_16x16x32_bf16 v[8:11], v[140:143], v[200:203], v[8:11]
	v_mfma_f32_16x16x32_bf16 v[12:15], v[132:135], v[200:203], v[12:15]
	v_mfma_f32_16x16x32_bf16 v[12:15], v[128:131], v[196:199], v[12:15]
	v_mfma_f32_16x16x32_bf16 v[52:55], v[144:147], v[160:163], v[52:55]
	v_mfma_f32_16x16x32_bf16 v[52:55], v[148:151], v[164:167], v[52:55]
	v_mfma_f32_16x16x32_bf16 v[48:51], v[156:159], v[164:167], v[48:51]
	v_mfma_f32_16x16x32_bf16 v[48:51], v[152:155], v[160:163], v[48:51]
	v_mfma_f32_16x16x32_bf16 v[32:35], v[152:155], v[168:171], v[32:35]
	v_mfma_f32_16x16x32_bf16 v[32:35], v[156:159], v[172:175], v[32:35]
	v_mfma_f32_16x16x32_bf16 v[36:39], v[148:151], v[172:175], v[36:39]
	v_mfma_f32_16x16x32_bf16 v[36:39], v[144:147], v[168:171], v[36:39]
	v_mfma_f32_16x16x32_bf16 v[20:23], v[144:147], v[176:179], v[20:23]
	v_mfma_f32_16x16x32_bf16 v[20:23], v[148:151], v[180:183], v[20:23]
	v_mfma_f32_16x16x32_bf16 v[16:19], v[156:159], v[180:183], v[16:19]
	v_mfma_f32_16x16x32_bf16 v[16:19], v[152:155], v[176:179], v[16:19]
	v_mfma_f32_16x16x32_bf16 v[0:3], v[152:155], v[196:199], v[0:3]
	v_mfma_f32_16x16x32_bf16 v[0:3], v[156:159], v[200:203], v[0:3]
	v_mfma_f32_16x16x32_bf16 v[4:7], v[148:151], v[200:203], v[4:7]
	v_mfma_f32_16x16x32_bf16 v[4:7], v[144:147], v[196:199], v[4:7]
	s_barrier
; #define PG8_STAGE(bufoff, gbase, voff) do { _Pragma("unroll") for (int _i = 0; _i < 2; ++_i) \
;         __builtin_amdgcn_global_load_lds((const unsigned*)((const char*)(gbase) + (voff)[_i]), (PG8_LAS unsigned*)(lds + (bufoff) + ldsw + _i * 8192), 16, 0, 0); } while (0)
; #define PG8_LDA(dst, b, h) do { _Pragma("unroll") for (int m = 0; m < 4; ++m) _Pragma("unroll") for (int k = 0; k < 2; ++k) dst[m][k] = *(const PG8_LAS bf16x8*)(lds + PG8_SA(b, h) + aoff + m * 2048 + k * 1024); } while (0)
; #define PG8_LDB(dst, b, h) do { _Pragma("unroll") for (int n = 0; n < 2; ++n) _Pragma("unroll") for (int k = 0; k < 2; ++k) dst[n][k] = *(const PG8_LAS bf16x8*)(lds + PG8_SB(b, h) + boff + n * 2048 + k * 1024); } while (0)
; #define PG8_MMA(ai, bj, At, Bt) do { __builtin_amdgcn_s_setprio(1); _Pragma("unroll") for (int m = 0; m < 4; ++m) _Pragma("unroll") for (int n = 0; n < 2; ++n) _Pragma("unroll") for (int k = 0; k < 2; ++k) \
;         acc[ai][bj][m][n] = __builtin_amdgcn_mfma_f32_16x16x32_bf16(Bt[n][k], At[m][k], acc[ai][bj][m][n], 0, 0, 0); __builtin_amdgcn_s_setprio(0); } while (0)
; #define PG8_WAIT_V(n) asm volatile("s_waitcnt vmcnt(" #n ")" ::: "memory")
; #define PG8_WAIT_L(n) asm volatile("s_waitcnt lgkmcnt(" #n ")" ::: "memory")
; #define PG8_BAR __builtin_amdgcn_s_barrier()
; #define PG8_SCHED __builtin_amdgcn_sched_barrier(0)
; template <class Epi, class Sched, bool ALIGN_EPI = false, bool SP2 = false>
; __device__ __forceinline__ void gemm_phase(PG8_LAS unsigned char* lds, const Gemm g, const Sched& S, const Epi& E, int wave_s) {
;     ...
;             PG8_LDB(B0, 1, 0); PG8_LDB(B1, 1, 1); PG8_SCHED; PG8_LDA(At, 1, 0); PG8_STAGE(PG8_SA(0, 1), a2 + hstep, voffA);
;             PG8_WAIT_V(8); PG8_WAIT_L(0); PG8_BAR; PG8_MMA(0, 0, At, B0); PG8_MMA(0, 1, At, B1); PG8_BAR; PG8_SCHED;
;             PG8_LDA(At, 1, 1); PG8_STAGE(PG8_SB(1, 0), b3, voffB); PG8_STAGE(PG8_SB(1, 1), b3 + hstep, voffB); PG8_STAGE(PG8_SA(1, 0), a3, voffA);
;             PG8_WAIT_V(8); PG8_WAIT_L(0); PG8_BAR; PG8_MMA(1, 0, At, B0); PG8_MMA(1, 1, At, B1); PG8_BAR; PG8_SCHED;
	s_add_i32 s45, 0, 0x18000
	s_add_i32 s86, 0, 0x1c000
	v_add_u32_e32 v140, s45, v210
	v_add_u32_e32 v156, s86, v210
	ds_read_b128 v[128:131], v140
	ds_read_b128 v[132:135], v140 offset:1024
	ds_read_b128 v[136:139], v140 offset:2048
	ds_read_b128 v[140:143], v140 offset:3072
	ds_read_b128 v[144:147], v156
	ds_read_b128 v[148:151], v156 offset:1024
	ds_read_b128 v[152:155], v156 offset:2048
	ds_read_b128 v[156:159], v156 offset:3072
	s_add_u32 s54, s54, 0x100000
	s_addc_u32 s55, s55, 0
	s_mov_b32 m0, s62
	s_nop 0
	ds_read_b128 v[160:163], v213 offset:32768
	ds_read_b128 v[164:167], v213 offset:33792
	ds_read_b128 v[168:171], v213 offset:34816
	ds_read_b128 v[172:175], v213 offset:35840
	ds_read_b128 v[176:179], v213 offset:36864
	ds_read_b128 v[180:183], v213 offset:37888
	ds_read_b128 v[196:199], v213 offset:38912
	ds_read_b128 v[200:203], v213 offset:39936
	global_load_lds_dwordx4 v184, s[54:55]
	s_mov_b32 m0, s63
	s_nop 0
	global_load_lds_dwordx4 v188, s[54:55]
	s_waitcnt vmcnt(8)
	s_waitcnt lgkmcnt(0)
	s_barrier
	v_mfma_f32_16x16x32_bf16 v[124:127], v[128:131], v[160:163], v[124:127]
	v_mfma_f32_16x16x32_bf16 v[124:127], v[132:135], v[164:167], v[124:127]
	v_mfma_f32_16x16x32_bf16 v[120:123], v[140:143], v[164:167], v[120:123]
	v_mfma_f32_16x16x32_bf16 v[120:123], v[136:139], v[160:163], v[120:123]
	v_mfma_f32_16x16x32_bf16 v[104:107], v[136:139], v[168:171], v[104:107]
	v_mfma_f32_16x16x32_bf16 v[104:107], v[140:143], v[172:175], v[104:107]
	v_mfma_f32_16x16x32_bf16 v[108:111], v[132:135], v[172:175], v[108:111]
	v_mfma_f32_16x16x32_bf16 v[108:111], v[128:131], v[168:171], v[108:111]
	v_mfma_f32_16x16x32_bf16 v[92:95], v[128:131], v[176:179], v[92:95]
	v_mfma_f32_16x16x32_bf16 v[92:95], v[132:135], v[180:183], v[92:95]
	v_mfma_f32_16x16x32_bf16 v[88:91], v[140:143], v[180:183], v[88:91]
	v_mfma_f32_16x16x32_bf16 v[88:91], v[136:139], v[176:179], v[88:91]
	v_mfma_f32_16x16x32_bf16 v[72:75], v[136:139], v[196:199], v[72:75]
	v_mfma_f32_16x16x32_bf16 v[72:75], v[140:143], v[200:203], v[72:75]
	v_mfma_f32_16x16x32_bf16 v[76:79], v[132:135], v[200:203], v[76:79]
	v_mfma_f32_16x16x32_bf16 v[76:79], v[128:131], v[196:199], v[76:79]
	v_mfma_f32_16x16x32_bf16 v[116:119], v[144:147], v[160:163], v[116:119]
	v_mfma_f32_16x16x32_bf16 v[116:119], v[148:151], v[164:167], v[116:119]
	v_mfma_f32_16x16x32_bf16 v[112:115], v[156:159], v[164:167], v[112:115]
	v_mfma_f32_16x16x32_bf16 v[112:115], v[152:155], v[160:163], v[112:115]
	v_mfma_f32_16x16x32_bf16 v[96:99], v[152:155], v[168:171], v[96:99]
	v_mfma_f32_16x16x32_bf16 v[96:99], v[156:159], v[172:175], v[96:99]
	v_mfma_f32_16x16x32_bf16 v[100:103], v[148:151], v[172:175], v[100:103]
	v_mfma_f32_16x16x32_bf16 v[100:103], v[144:147], v[168:171], v[100:103]
	v_mfma_f32_16x16x32_bf16 v[84:87], v[144:147], v[176:179], v[84:87]
	v_mfma_f32_16x16x32_bf16 v[84:87], v[148:151], v[180:183], v[84:87]
	v_mfma_f32_16x16x32_bf16 v[80:83], v[156:159], v[180:183], v[80:83]
	v_mfma_f32_16x16x32_bf16 v[80:83], v[152:155], v[176:179], v[80:83]
	v_mfma_f32_16x16x32_bf16 v[64:67], v[152:155], v[196:199], v[64:67]
	v_mfma_f32_16x16x32_bf16 v[64:67], v[156:159], v[200:203], v[64:67]
	v_mfma_f32_16x16x32_bf16 v[68:71], v[148:151], v[200:203], v[68:71]
	v_mfma_f32_16x16x32_bf16 v[68:71], v[144:147], v[196:199], v[68:71]
	s_barrier
	s_add_i32 s45, s45, s60
	s_mov_b32 m0, s45
	ds_read_b128 v[160:163], v213 offset:49152
	ds_read_b128 v[164:167], v213 offset:50176
	ds_read_b128 v[168:171], v213 offset:51200
	ds_read_b128 v[172:175], v213 offset:52224
	ds_read_b128 v[176:179], v213 offset:53248
	ds_read_b128 v[180:183], v213 offset:54272
	ds_read_b128 v[196:199], v213 offset:55296
	ds_read_b128 v[200:203], v213 offset:56320
	s_add_u32 s94, s52, 0x80
	s_addc_u32 s95, s53, 0
	global_load_lds_dwordx4 v186, s[94:95]
	s_add_i32 m0, s45, 0x2000
	s_add_u32 s52, s52, 0x100080
	s_addc_u32 s53, s53, 0
	s_add_i32 s45, s86, s60
	global_load_lds_dwordx4 v190, s[94:95]
	s_mov_b32 m0, s45
	s_nop 0
	global_load_lds_dwordx4 v186, s[52:53]
	s_add_i32 m0, s45, 0x2000
	s_nop 0
	global_load_lds_dwordx4 v190, s[52:53]
	s_mov_b32 m0, s70
	s_nop 0
	s_add_u32 s96, s54, 0xfff00080
	s_addc_u32 s97, s55, -1
	global_load_lds_dwordx4 v184, s[96:97]
	s_mov_b32 m0, s71
	s_nop 0
	global_load_lds_dwordx4 v188, s[96:97]
	s_waitcnt vmcnt(8)
	s_waitcnt lgkmcnt(0)
	s_barrier
	v_mfma_f32_16x16x32_bf16 v[60:63], v[128:131], v[160:163], v[60:63]
	v_mfma_f32_16x16x32_bf16 v[60:63], v[132:135], v[164:167], v[60:63]
	v_mfma_f32_16x16x32_bf16 v[56:59], v[140:143], v[164:167], v[56:59]
	v_mfma_f32_16x16x32_bf16 v[56:59], v[136:139], v[160:163], v[56:59]
	v_mfma_f32_16x16x32_bf16 v[40:43], v[136:139], v[168:171], v[40:43]
	v_mfma_f32_16x16x32_bf16 v[40:43], v[140:143], v[172:175], v[40:43]
	v_mfma_f32_16x16x32_bf16 v[44:47], v[132:135], v[172:175], v[44:47]
	v_mfma_f32_16x16x32_bf16 v[44:47], v[128:131], v[168:171], v[44:47]
	v_mfma_f32_16x16x32_bf16 v[28:31], v[128:131], v[176:179], v[28:31]
	v_mfma_f32_16x16x32_bf16 v[28:31], v[132:135], v[180:183], v[28:31]
	v_mfma_f32_16x16x32_bf16 v[24:27], v[140:143], v[180:183], v[24:27]
	v_mfma_f32_16x16x32_bf16 v[24:27], v[136:139], v[176:179], v[24:27]
	v_mfma_f32_16x16x32_bf16 v[8:11], v[136:139], v[196:199], v[8:11]
	v_mfma_f32_16x16x32_bf16 v[8:11], v[140:143], v[200:203], v[8:11]
	v_mfma_f32_16x16x32_bf16 v[12:15], v[132:135], v[200:203], v[12:15]
	v_mfma_f32_16x16x32_bf16 v[12:15], v[128:131], v[196:199], v[12:15]
	v_mfma_f32_16x16x32_bf16 v[52:55], v[144:147], v[160:163], v[52:55]
	v_mfma_f32_16x16x32_bf16 v[52:55], v[148:151], v[164:167], v[52:55]
	v_mfma_f32_16x16x32_bf16 v[48:51], v[156:159], v[164:167], v[48:51]
	v_mfma_f32_16x16x32_bf16 v[48:51], v[152:155], v[160:163], v[48:51]
	v_mfma_f32_16x16x32_bf16 v[32:35], v[152:155], v[168:171], v[32:35]
	v_mfma_f32_16x16x32_bf16 v[32:35], v[156:159], v[172:175], v[32:35]
	v_mfma_f32_16x16x32_bf16 v[36:39], v[148:151], v[172:175], v[36:39]
	v_mfma_f32_16x16x32_bf16 v[36:39], v[144:147], v[168:171], v[36:39]
	v_mfma_f32_16x16x32_bf16 v[20:23], v[144:147], v[176:179], v[20:23]
	v_mfma_f32_16x16x32_bf16 v[20:23], v[148:151], v[180:183], v[20:23]
	v_mfma_f32_16x16x32_bf16 v[16:19], v[156:159], v[180:183], v[16:19]
	v_mfma_f32_16x16x32_bf16 v[16:19], v[152:155], v[176:179], v[16:19]
	v_mfma_f32_16x16x32_bf16 v[0:3], v[152:155], v[196:199], v[0:3]
	v_mfma_f32_16x16x32_bf16 v[0:3], v[156:159], v[200:203], v[0:3]
	v_mfma_f32_16x16x32_bf16 v[4:7], v[148:151], v[200:203], v[4:7]
	v_mfma_f32_16x16x32_bf16 v[4:7], v[144:147], v[196:199], v[4:7]
	s_barrier
	s_add_i32 s45, s43, 2
	s_add_u32 s50, s50, 0x100
	s_addc_u32 s51, s51, 0
	s_add_u32 s7, s7, 0x100
	s_addc_u32 s41, s41, 0
	s_cmp_ge_i32 s43, s85
	s_mov_b32 s43, s45
	s_cbranch_scc0 .LBB0_1200
	s_and_b64 vcc, exec, s[20:21]
	s_cbranch_vccz .LBB0_1203
	s_barrier

; #define PG8_STAGE(bufoff, gbase, voff) do { _Pragma("unroll") for (int _i = 0; _i < 2; ++_i) \
;         __builtin_amdgcn_global_load_lds((const unsigned*)((const char*)(gbase) + (voff)[_i]), (PG8_LAS unsigned*)(lds + (bufoff) + ldsw + _i * 8192), 16, 0, 0); } while (0)
; #define PG8_LDA(dst, b, h) do { _Pragma("unroll") for (int m = 0; m < 4; ++m) _Pragma("unroll") for (int k = 0; k < 2; ++k) dst[m][k] = *(const PG8_LAS bf16x8*)(lds + PG8_SA(b, h) + aoff + m * 2048 + k * 1024); } while (0)
; #define PG8_LDB(dst, b, h) do { _Pragma("unroll") for (int n = 0; n < 2; ++n) _Pragma("unroll") for (int k = 0; k < 2; ++k) dst[n][k] = *(const PG8_LAS bf16x8*)(lds + PG8_SB(b, h) + boff + n * 2048 + k * 1024); } while (0)
; #define PG8_MMA(ai, bj, At, Bt) do { __builtin_amdgcn_s_setprio(1); _Pragma("unroll") for (int m = 0; m < 4; ++m) _Pragma("unroll") for (int n = 0; n < 2; ++n) _Pragma("unroll") for (int k = 0; k < 2; ++k) \
;         acc[ai][bj][m][n] = __builtin_amdgcn_mfma_f32_16x16x32_bf16(Bt[n][k], At[m][k], acc[ai][bj][m][n], 0, 0, 0); __builtin_amdgcn_s_setprio(0); } while (0)
; #define PG8_WAIT_V(n) asm volatile("s_waitcnt vmcnt(" #n ")" ::: "memory")
; #define PG8_WAIT_L(n) asm volatile("s_waitcnt lgkmcnt(" #n ")" ::: "memory")
; #define PG8_BAR __builtin_amdgcn_s_barrier()
; #define PG8_SCHED __builtin_amdgcn_sched_barrier(0)
; template <class Epi, class Sched, bool ALIGN_EPI = false, bool SP2 = false>
; __device__ __forceinline__ void gemm_phase(PG8_LAS unsigned char* lds, const Gemm g, const Sched& S, const Epi& E, int wave_s) {
;     ...
;             PG8_LDB(B0, 0, 0); PG8_LDB(B1, 0, 1); PG8_SCHED; PG8_LDA(At, 0, 0); PG8_STAGE(PG8_SA(1, 1), a1 + hstep, voffA);
;             PG8_WAIT_V(8); PG8_WAIT_L(0); PG8_BAR; PG8_MMA(0, 0, At, B0); PG8_MMA(0, 1, At, B1); PG8_BAR; PG8_SCHED;
;             PG8_LDA(At, 0, 1); PG8_STAGE(PG8_SB(0, 0), b2, voffB); PG8_STAGE(PG8_SB(0, 1), b2 + hstep, voffB); PG8_STAGE(PG8_SA(0, 0), a2, voffA);
;             PG8_WAIT_V(8); PG8_WAIT_L(0); PG8_BAR; PG8_MMA(1, 0, At, B0); PG8_MMA(1, 1, At, B1); PG8_BAR; PG8_SCHED;
.LBB0_1343:
	ds_read_b128 v[144:147], v150 offset:3072
	ds_read_b128 v[152:155], v150 offset:2048
	ds_read_b128 v[156:159], v150 offset:1024
	ds_read_b128 v[160:163], v150
	ds_read_b128 v[164:167], v149 offset:3072
	ds_read_b128 v[168:171], v149 offset:2048
	ds_read_b128 v[172:175], v149 offset:1024
	ds_read_b128 v[176:179], v149
	s_add_u32 s46, s44, 0xfff00080
	s_addc_u32 s47, s45, -1
	s_cmp_eq_u32 s88, 60
	s_cselect_b32 s49, s29, s47
	s_cselect_b32 s48, s74, s46
	s_cselect_b32 s47, s35, s87
	s_cselect_b32 s46, s75, s86
	s_mov_b32 m0, s76
	s_nop 0
	ds_read_b128 v[180:183], v151
	ds_read_b128 v[184:187], v151 offset:1024
	ds_read_b128 v[188:191], v151 offset:2048
	ds_read_b128 v[192:195], v151 offset:3072
	ds_read_b128 v[196:199], v151 offset:4096
	ds_read_b128 v[200:203], v151 offset:5120
	ds_read_b128 v[204:207], v151 offset:6144
	ds_read_b128 v[208:211], v151 offset:7168
	global_load_lds_dwordx4 v138, s[44:45]
	s_mov_b32 m0, s77
	s_nop 0
	global_load_lds_dwordx4 v140, s[44:45]
	s_waitcnt vmcnt(8)
	s_waitcnt lgkmcnt(0)
	s_barrier
	v_mfma_f32_16x16x32_bf16 v[124:127], v[176:179], v[180:183], v[124:127]
	v_mfma_f32_16x16x32_bf16 v[124:127], v[172:175], v[184:187], v[124:127]
	v_mfma_f32_16x16x32_bf16 v[120:123], v[164:167], v[184:187], v[120:123]
	v_mfma_f32_16x16x32_bf16 v[120:123], v[168:171], v[180:183], v[120:123]
	v_mfma_f32_16x16x32_bf16 v[104:107], v[168:171], v[188:191], v[104:107]
	v_mfma_f32_16x16x32_bf16 v[104:107], v[164:167], v[192:195], v[104:107]
	v_mfma_f32_16x16x32_bf16 v[108:111], v[172:175], v[192:195], v[108:111]
	v_mfma_f32_16x16x32_bf16 v[108:111], v[176:179], v[188:191], v[108:111]
	v_mfma_f32_16x16x32_bf16 v[92:95], v[176:179], v[196:199], v[92:95]
	v_mfma_f32_16x16x32_bf16 v[92:95], v[172:175], v[200:203], v[92:95]
	v_mfma_f32_16x16x32_bf16 v[88:91], v[164:167], v[200:203], v[88:91]
	v_mfma_f32_16x16x32_bf16 v[88:91], v[168:171], v[196:199], v[88:91]
	v_mfma_f32_16x16x32_bf16 v[72:75], v[168:171], v[204:207], v[72:75]
	v_mfma_f32_16x16x32_bf16 v[72:75], v[164:167], v[208:211], v[72:75]
	v_mfma_f32_16x16x32_bf16 v[76:79], v[172:175], v[208:211], v[76:79]
	v_mfma_f32_16x16x32_bf16 v[76:79], v[176:179], v[204:207], v[76:79]
	v_mfma_f32_16x16x32_bf16 v[116:119], v[160:163], v[180:183], v[116:119]
	v_mfma_f32_16x16x32_bf16 v[116:119], v[156:159], v[184:187], v[116:119]
	v_mfma_f32_16x16x32_bf16 v[112:115], v[144:147], v[184:187], v[112:115]
	v_mfma_f32_16x16x32_bf16 v[112:115], v[152:155], v[180:183], v[112:115]
	v_mfma_f32_16x16x32_bf16 v[96:99], v[152:155], v[188:191], v[96:99]
	v_mfma_f32_16x16x32_bf16 v[96:99], v[144:147], v[192:195], v[96:99]
	v_mfma_f32_16x16x32_bf16 v[100:103], v[156:159], v[192:195], v[100:103]
	v_mfma_f32_16x16x32_bf16 v[100:103], v[160:163], v[188:191], v[100:103]
	v_mfma_f32_16x16x32_bf16 v[84:87], v[160:163], v[196:199], v[84:87]
	v_mfma_f32_16x16x32_bf16 v[84:87], v[156:159], v[200:203], v[84:87]
	v_mfma_f32_16x16x32_bf16 v[80:83], v[144:147], v[200:203], v[80:83]
	v_mfma_f32_16x16x32_bf16 v[80:83], v[152:155], v[196:199], v[80:83]
	v_mfma_f32_16x16x32_bf16 v[64:67], v[152:155], v[204:207], v[64:67]
	v_mfma_f32_16x16x32_bf16 v[64:67], v[144:147], v[208:211], v[64:67]
	v_mfma_f32_16x16x32_bf16 v[68:71], v[156:159], v[208:211], v[68:71]
	v_mfma_f32_16x16x32_bf16 v[68:71], v[160:163], v[204:207], v[68:71]
	s_barrier
	s_mov_b32 m0, s78
	s_nop 0
	s_add_u32 s90, s46, 0x100000
	ds_read_b128 v[180:183], v151 offset:16384
	ds_read_b128 v[184:187], v151 offset:17408
	ds_read_b128 v[188:191], v151 offset:18432
	ds_read_b128 v[192:195], v151 offset:19456
	ds_read_b128 v[196:199], v151 offset:20480
	ds_read_b128 v[200:203], v151 offset:21504
	ds_read_b128 v[204:207], v151 offset:22528
	ds_read_b128 v[208:211], v151 offset:23552
	global_load_lds_dwordx4 v132, s[46:47]
	s_mov_b32 m0, s79
	s_addc_u32 s91, s47, 0
	global_load_lds_dwordx4 v128, s[46:47]
	s_mov_b32 m0, s80
	s_nop 0
	global_load_lds_dwordx4 v132, s[90:91]
	s_mov_b32 m0, s81
	s_nop 0
	global_load_lds_dwordx4 v128, s[90:91]
	s_mov_b32 m0, s41
	s_nop 0
	global_load_lds_dwordx4 v134, s[48:49]
	s_mov_b32 m0, s43
	s_nop 0
	global_load_lds_dwordx4 v130, s[48:49]
	s_waitcnt vmcnt(8)
	s_waitcnt lgkmcnt(0)
	s_barrier
	v_mfma_f32_16x16x32_bf16 v[60:63], v[176:179], v[180:183], v[60:63]
	v_mfma_f32_16x16x32_bf16 v[60:63], v[172:175], v[184:187], v[60:63]
	v_mfma_f32_16x16x32_bf16 v[56:59], v[164:167], v[184:187], v[56:59]
	v_mfma_f32_16x16x32_bf16 v[56:59], v[168:171], v[180:183], v[56:59]
	v_mfma_f32_16x16x32_bf16 v[40:43], v[168:171], v[188:191], v[40:43]
	v_mfma_f32_16x16x32_bf16 v[40:43], v[164:167], v[192:195], v[40:43]
	v_mfma_f32_16x16x32_bf16 v[44:47], v[172:175], v[192:195], v[44:47]
	v_mfma_f32_16x16x32_bf16 v[44:47], v[176:179], v[188:191], v[44:47]
	v_mfma_f32_16x16x32_bf16 v[28:31], v[176:179], v[196:199], v[28:31]
	v_mfma_f32_16x16x32_bf16 v[28:31], v[172:175], v[200:203], v[28:31]
	v_mfma_f32_16x16x32_bf16 v[24:27], v[164:167], v[200:203], v[24:27]
	v_mfma_f32_16x16x32_bf16 v[24:27], v[168:171], v[196:199], v[24:27]
	v_mfma_f32_16x16x32_bf16 v[8:11], v[168:171], v[204:207], v[8:11]
	v_mfma_f32_16x16x32_bf16 v[8:11], v[164:167], v[208:211], v[8:11]
	v_mfma_f32_16x16x32_bf16 v[12:15], v[172:175], v[208:211], v[12:15]
	v_mfma_f32_16x16x32_bf16 v[12:15], v[176:179], v[204:207], v[12:15]
	v_mfma_f32_16x16x32_bf16 v[52:55], v[160:163], v[180:183], v[52:55]
	v_mfma_f32_16x16x32_bf16 v[52:55], v[156:159], v[184:187], v[52:55]
	v_mfma_f32_16x16x32_bf16 v[48:51], v[144:147], v[184:187], v[48:51]
	v_mfma_f32_16x16x32_bf16 v[48:51], v[152:155], v[180:183], v[48:51]
	v_mfma_f32_16x16x32_bf16 v[32:35], v[152:155], v[188:191], v[32:35]
	v_mfma_f32_16x16x32_bf16 v[32:35], v[144:147], v[192:195], v[32:35]
	v_mfma_f32_16x16x32_bf16 v[36:39], v[156:159], v[192:195], v[36:39]
	v_mfma_f32_16x16x32_bf16 v[36:39], v[160:163], v[188:191], v[36:39]
	v_mfma_f32_16x16x32_bf16 v[20:23], v[160:163], v[196:199], v[20:23]
	v_mfma_f32_16x16x32_bf16 v[20:23], v[156:159], v[200:203], v[20:23]
	v_mfma_f32_16x16x32_bf16 v[16:19], v[144:147], v[200:203], v[16:19]
	v_mfma_f32_16x16x32_bf16 v[16:19], v[152:155], v[196:199], v[16:19]
	v_mfma_f32_16x16x32_bf16 v[0:3], v[152:155], v[204:207], v[0:3]
	v_mfma_f32_16x16x32_bf16 v[0:3], v[144:147], v[208:211], v[0:3]
	v_mfma_f32_16x16x32_bf16 v[4:7], v[156:159], v[208:211], v[4:7]
	v_mfma_f32_16x16x32_bf16 v[4:7], v[160:163], v[204:207], v[4:7]
	s_barrier
; #define PG8_STAGE(bufoff, gbase, voff) do { _Pragma("unroll") for (int _i = 0; _i < 2; ++_i) \
;         __builtin_amdgcn_global_load_lds((const unsigned*)((const char*)(gbase) + (voff)[_i]), (PG8_LAS unsigned*)(lds + (bufoff) + ldsw + _i * 8192), 16, 0, 0); } while (0)
; #define PG8_LDA(dst, b, h) do { _Pragma("unroll") for (int m = 0; m < 4; ++m) _Pragma("unroll") for (int k = 0; k < 2; ++k) dst[m][k] = *(const PG8_LAS bf16x8*)(lds + PG8_SA(b, h) + aoff + m * 2048 + k * 1024); } while (0)
; #define PG8_LDB(dst, b, h) do { _Pragma("unroll") for (int n = 0; n < 2; ++n) _Pragma("unroll") for (int k = 0; k < 2; ++k) dst[n][k] = *(const PG8_LAS bf16x8*)(lds + PG8_SB(b, h) + boff + n * 2048 + k * 1024); } while (0)
; #define PG8_MMA(ai, bj, At, Bt) do { __builtin_amdgcn_s_setprio(1); _Pragma("unroll") for (int m = 0; m < 4; ++m) _Pragma("unroll") for (int n = 0; n < 2; ++n) _Pragma("unroll") for (int k = 0; k < 2; ++k) \
;         acc[ai][bj][m][n] = __builtin_amdgcn_mfma_f32_16x16x32_bf16(Bt[n][k], At[m][k], acc[ai][bj][m][n], 0, 0, 0); __builtin_amdgcn_s_setprio(0); } while (0)
; #define PG8_WAIT_V(n) asm volatile("s_waitcnt vmcnt(" #n ")" ::: "memory")
; #define PG8_WAIT_L(n) asm volatile("s_waitcnt lgkmcnt(" #n ")" ::: "memory")
; #define PG8_BAR __builtin_amdgcn_s_barrier()
; #define PG8_SCHED __builtin_amdgcn_sched_barrier(0)
; template <class Epi, class Sched, bool ALIGN_EPI = false, bool SP2 = false>
; __device__ __forceinline__ void gemm_phase(PG8_LAS unsigned char* lds, const Gemm g, const Sched& S, const Epi& E, int wave_s) {
;     ...
;             PG8_LDB(B0, 1, 0); PG8_LDB(B1, 1, 1); PG8_SCHED; PG8_LDA(At, 1, 0); PG8_STAGE(PG8_SA(0, 1), a2 + hstep, voffA);
;             PG8_WAIT_V(8); PG8_WAIT_L(0); PG8_BAR; PG8_MMA(0, 0, At, B0); PG8_MMA(0, 1, At, B1); PG8_BAR; PG8_SCHED;
;             PG8_LDA(At, 1, 1); PG8_STAGE(PG8_SB(1, 0), b3, voffB); PG8_STAGE(PG8_SB(1, 1), b3 + hstep, voffB); PG8_STAGE(PG8_SA(1, 0), a3, voffA);
;             PG8_WAIT_V(8); PG8_WAIT_L(0); PG8_BAR; PG8_MMA(1, 0, At, B0); PG8_MMA(1, 1, At, B1); PG8_BAR; PG8_SCHED;
	ds_read_b128 v[144:147], v142
	ds_read_b128 v[152:155], v142 offset:1024
	ds_read_b128 v[156:159], v142 offset:2048
	ds_read_b128 v[160:163], v142 offset:3072
	ds_read_b128 v[164:167], v143
	ds_read_b128 v[168:171], v143 offset:1024
	ds_read_b128 v[172:175], v143 offset:2048
	ds_read_b128 v[176:179], v143 offset:3072
	s_add_u32 s48, s48, 0x100000
	s_addc_u32 s49, s49, 0
	s_mov_b32 m0, s58
	s_nop 0
	ds_read_b128 v[180:183], v151 offset:32768
	ds_read_b128 v[184:187], v151 offset:33792
	ds_read_b128 v[188:191], v151 offset:34816
	ds_read_b128 v[192:195], v151 offset:35840
	ds_read_b128 v[196:199], v151 offset:36864
	ds_read_b128 v[200:203], v151 offset:37888
	ds_read_b128 v[204:207], v151 offset:38912
	ds_read_b128 v[208:211], v151 offset:39936
	global_load_lds_dwordx4 v134, s[48:49]
	s_mov_b32 m0, s59
	s_nop 0
	global_load_lds_dwordx4 v130, s[48:49]
	s_waitcnt vmcnt(8)
	s_waitcnt lgkmcnt(0)
	s_barrier
	v_mfma_f32_16x16x32_bf16 v[124:127], v[144:147], v[180:183], v[124:127]
	v_mfma_f32_16x16x32_bf16 v[124:127], v[152:155], v[184:187], v[124:127]
	v_mfma_f32_16x16x32_bf16 v[120:123], v[160:163], v[184:187], v[120:123]
	v_mfma_f32_16x16x32_bf16 v[120:123], v[156:159], v[180:183], v[120:123]
	v_mfma_f32_16x16x32_bf16 v[104:107], v[156:159], v[188:191], v[104:107]
	v_mfma_f32_16x16x32_bf16 v[104:107], v[160:163], v[192:195], v[104:107]
	v_mfma_f32_16x16x32_bf16 v[108:111], v[152:155], v[192:195], v[108:111]
	v_mfma_f32_16x16x32_bf16 v[108:111], v[144:147], v[188:191], v[108:111]
	v_mfma_f32_16x16x32_bf16 v[92:95], v[144:147], v[196:199], v[92:95]
	v_mfma_f32_16x16x32_bf16 v[92:95], v[152:155], v[200:203], v[92:95]
	v_mfma_f32_16x16x32_bf16 v[88:91], v[160:163], v[200:203], v[88:91]
	v_mfma_f32_16x16x32_bf16 v[88:91], v[156:159], v[196:199], v[88:91]
	v_mfma_f32_16x16x32_bf16 v[72:75], v[156:159], v[204:207], v[72:75]
	v_mfma_f32_16x16x32_bf16 v[72:75], v[160:163], v[208:211], v[72:75]
	v_mfma_f32_16x16x32_bf16 v[76:79], v[152:155], v[208:211], v[76:79]
	v_mfma_f32_16x16x32_bf16 v[76:79], v[144:147], v[204:207], v[76:79]
	v_mfma_f32_16x16x32_bf16 v[116:119], v[164:167], v[180:183], v[116:119]
	v_mfma_f32_16x16x32_bf16 v[116:119], v[168:171], v[184:187], v[116:119]
	v_mfma_f32_16x16x32_bf16 v[112:115], v[176:179], v[184:187], v[112:115]
	v_mfma_f32_16x16x32_bf16 v[112:115], v[172:175], v[180:183], v[112:115]
	v_mfma_f32_16x16x32_bf16 v[96:99], v[172:175], v[188:191], v[96:99]
	v_mfma_f32_16x16x32_bf16 v[96:99], v[176:179], v[192:195], v[96:99]
	v_mfma_f32_16x16x32_bf16 v[100:103], v[168:171], v[192:195], v[100:103]
	v_mfma_f32_16x16x32_bf16 v[100:103], v[164:167], v[188:191], v[100:103]
	v_mfma_f32_16x16x32_bf16 v[84:87], v[164:167], v[196:199], v[84:87]
	v_mfma_f32_16x16x32_bf16 v[84:87], v[168:171], v[200:203], v[84:87]
	v_mfma_f32_16x16x32_bf16 v[80:83], v[176:179], v[200:203], v[80:83]
	v_mfma_f32_16x16x32_bf16 v[80:83], v[172:175], v[196:199], v[80:83]
	v_mfma_f32_16x16x32_bf16 v[64:67], v[172:175], v[204:207], v[64:67]
	v_mfma_f32_16x16x32_bf16 v[64:67], v[176:179], v[208:211], v[64:67]
	v_mfma_f32_16x16x32_bf16 v[68:71], v[168:171], v[208:211], v[68:71]
	v_mfma_f32_16x16x32_bf16 v[68:71], v[164:167], v[204:207], v[68:71]
	s_barrier
	s_mov_b32 m0, s82
	s_nop 0
	s_add_u32 s94, s46, 0x80
	s_addc_u32 s95, s47, 0
	s_add_u32 s46, s46, 0x100080
	ds_read_b128 v[180:183], v151 offset:49152
	ds_read_b128 v[184:187], v151 offset:50176
	ds_read_b128 v[188:191], v151 offset:51200
	ds_read_b128 v[192:195], v151 offset:52224
	ds_read_b128 v[196:199], v151 offset:53248
	ds_read_b128 v[200:203], v151 offset:54272
	ds_read_b128 v[204:207], v151 offset:55296
	ds_read_b128 v[208:211], v151 offset:56320
	global_load_lds_dwordx4 v132, s[94:95]
	s_mov_b32 m0, s83
	s_addc_u32 s47, s47, 0
	global_load_lds_dwordx4 v128, s[94:95]
	s_mov_b32 m0, s84
	s_nop 0
	global_load_lds_dwordx4 v132, s[46:47]
	s_mov_b32 m0, s85
	s_nop 0
	global_load_lds_dwordx4 v128, s[46:47]
	s_mov_b32 m0, s62
	s_nop 0
	s_add_u32 s96, s48, 0xfff00080
	s_addc_u32 s97, s49, -1
	global_load_lds_dwordx4 v134, s[96:97]
	s_mov_b32 m0, s63
	s_nop 0
	global_load_lds_dwordx4 v130, s[96:97]
	s_waitcnt vmcnt(8)
	s_waitcnt lgkmcnt(0)
	s_barrier
	v_mfma_f32_16x16x32_bf16 v[60:63], v[144:147], v[180:183], v[60:63]
	v_mfma_f32_16x16x32_bf16 v[60:63], v[152:155], v[184:187], v[60:63]
	v_mfma_f32_16x16x32_bf16 v[56:59], v[160:163], v[184:187], v[56:59]
	v_mfma_f32_16x16x32_bf16 v[56:59], v[156:159], v[180:183], v[56:59]
	v_mfma_f32_16x16x32_bf16 v[40:43], v[156:159], v[188:191], v[40:43]
	v_mfma_f32_16x16x32_bf16 v[40:43], v[160:163], v[192:195], v[40:43]
	v_mfma_f32_16x16x32_bf16 v[44:47], v[152:155], v[192:195], v[44:47]
	v_mfma_f32_16x16x32_bf16 v[44:47], v[144:147], v[188:191], v[44:47]
	v_mfma_f32_16x16x32_bf16 v[28:31], v[144:147], v[196:199], v[28:31]
	v_mfma_f32_16x16x32_bf16 v[28:31], v[152:155], v[200:203], v[28:31]
	v_mfma_f32_16x16x32_bf16 v[24:27], v[160:163], v[200:203], v[24:27]
	v_mfma_f32_16x16x32_bf16 v[24:27], v[156:159], v[196:199], v[24:27]
	v_mfma_f32_16x16x32_bf16 v[8:11], v[156:159], v[204:207], v[8:11]
	v_mfma_f32_16x16x32_bf16 v[8:11], v[160:163], v[208:211], v[8:11]
	v_mfma_f32_16x16x32_bf16 v[12:15], v[152:155], v[208:211], v[12:15]
	v_mfma_f32_16x16x32_bf16 v[12:15], v[144:147], v[204:207], v[12:15]
	v_mfma_f32_16x16x32_bf16 v[52:55], v[164:167], v[180:183], v[52:55]
	v_mfma_f32_16x16x32_bf16 v[52:55], v[168:171], v[184:187], v[52:55]
	v_mfma_f32_16x16x32_bf16 v[48:51], v[176:179], v[184:187], v[48:51]
	v_mfma_f32_16x16x32_bf16 v[48:51], v[172:175], v[180:183], v[48:51]
	v_mfma_f32_16x16x32_bf16 v[32:35], v[172:175], v[188:191], v[32:35]
	v_mfma_f32_16x16x32_bf16 v[32:35], v[176:179], v[192:195], v[32:35]
	v_mfma_f32_16x16x32_bf16 v[36:39], v[168:171], v[192:195], v[36:39]
	v_mfma_f32_16x16x32_bf16 v[36:39], v[164:167], v[188:191], v[36:39]
	v_mfma_f32_16x16x32_bf16 v[20:23], v[164:167], v[196:199], v[20:23]
	v_mfma_f32_16x16x32_bf16 v[20:23], v[168:171], v[200:203], v[20:23]
	v_mfma_f32_16x16x32_bf16 v[16:19], v[176:179], v[200:203], v[16:19]
	v_mfma_f32_16x16x32_bf16 v[16:19], v[172:175], v[196:199], v[16:19]
	v_mfma_f32_16x16x32_bf16 v[0:3], v[172:175], v[204:207], v[0:3]
	v_mfma_f32_16x16x32_bf16 v[0:3], v[176:179], v[208:211], v[0:3]
	v_mfma_f32_16x16x32_bf16 v[4:7], v[168:171], v[208:211], v[4:7]
	v_mfma_f32_16x16x32_bf16 v[4:7], v[164:167], v[204:207], v[4:7]
	s_barrier
	s_add_i32 s88, s88, 2
	s_add_u32 s44, s44, 0x100
	s_addc_u32 s45, s45, 0
	s_add_u32 s86, s86, 0x100
	s_addc_u32 s87, s87, 0
	s_cmp_gt_u32 s88, 61
	s_cbranch_scc0 .LBB0_1343
	s_and_b64 vcc, exec, s[14:15]
	s_cbranch_vccz .LBB0_1346
	s_barrier

; #define PG8_STAGE(bufoff, gbase, voff) do { _Pragma("unroll") for (int _i = 0; _i < 2; ++_i) \
;         __builtin_amdgcn_global_load_lds((const unsigned*)((const char*)(gbase) + (voff)[_i]), (PG8_LAS unsigned*)(lds + (bufoff) + ldsw + _i * 8192), 16, 0, 0); } while (0)
; #define PG8_LDA(dst, b, h) do { _Pragma("unroll") for (int m = 0; m < 4; ++m) _Pragma("unroll") for (int k = 0; k < 2; ++k) dst[m][k] = *(const PG8_LAS bf16x8*)(lds + PG8_SA(b, h) + aoff + m * 2048 + k * 1024); } while (0)
; #define PG8_LDB(dst, b, h) do { _Pragma("unroll") for (int n = 0; n < 2; ++n) _Pragma("unroll") for (int k = 0; k < 2; ++k) dst[n][k] = *(const PG8_LAS bf16x8*)(lds + PG8_SB(b, h) + boff + n * 2048 + k * 1024); } while (0)
; #define PG8_MMA(ai, bj, At, Bt) do { __builtin_amdgcn_s_setprio(1); _Pragma("unroll") for (int m = 0; m < 4; ++m) _Pragma("unroll") for (int n = 0; n < 2; ++n) _Pragma("unroll") for (int k = 0; k < 2; ++k) \
;         acc[ai][bj][m][n] = __builtin_amdgcn_mfma_f32_16x16x32_bf16(Bt[n][k], At[m][k], acc[ai][bj][m][n], 0, 0, 0); __builtin_amdgcn_s_setprio(0); } while (0)
; #define PG8_WAIT_V(n) asm volatile("s_waitcnt vmcnt(" #n ")" ::: "memory")
; #define PG8_WAIT_L(n) asm volatile("s_waitcnt lgkmcnt(" #n ")" ::: "memory")
; #define PG8_BAR __builtin_amdgcn_s_barrier()
; #define PG8_SCHED __builtin_amdgcn_sched_barrier(0)
; template <class Epi, class Sched, bool ALIGN_EPI = false, bool SP2 = false>
; __device__ __forceinline__ void gemm_phase(PG8_LAS unsigned char* lds, const Gemm g, const Sched& S, const Epi& E, int wave_s) {
;     ...
;             PG8_LDB(B0, 0, 0); PG8_LDB(B1, 0, 1); PG8_SCHED; PG8_LDA(At, 0, 0); PG8_STAGE(PG8_SA(1, 1), a1 + hstep, voffA);
;             PG8_WAIT_V(8); PG8_WAIT_L(0); PG8_BAR; PG8_MMA(0, 0, At, B0); PG8_MMA(0, 1, At, B1); PG8_BAR; PG8_SCHED;
;             PG8_LDA(At, 0, 1); PG8_STAGE(PG8_SB(0, 0), b2, voffB); PG8_STAGE(PG8_SB(0, 1), b2 + hstep, voffB); PG8_STAGE(PG8_SA(0, 0), a2, voffA);
;             PG8_WAIT_V(8); PG8_WAIT_L(0); PG8_BAR; PG8_MMA(1, 0, At, B0); PG8_MMA(1, 1, At, B1); PG8_BAR; PG8_SCHED;
.LBB0_1410:
	ds_read_b128 v[128:131], v211
	ds_read_b128 v[132:135], v211 offset:1024
	ds_read_b128 v[136:139], v211 offset:2048
	ds_read_b128 v[140:143], v211 offset:3072
	ds_read_b128 v[144:147], v212
	ds_read_b128 v[148:151], v212 offset:1024
	ds_read_b128 v[152:155], v212 offset:2048
	ds_read_b128 v[156:159], v212 offset:3072
	s_add_u32 s45, s50, 0xffc00080
	s_addc_u32 s52, s51, -1
	s_cmp_eq_u32 s85, s43
	s_cselect_b32 s55, s47, s52
	s_cselect_b32 s54, s46, s45
	s_cselect_b32 s53, s49, s41
	s_cselect_b32 s52, s48, s7
	s_add_i32 m0, s9, 0xc000
	ds_read_b128 v[160:163], v213
	ds_read_b128 v[164:167], v213 offset:1024
	ds_read_b128 v[168:171], v213 offset:2048
	ds_read_b128 v[172:175], v213 offset:3072
	ds_read_b128 v[176:179], v213 offset:4096
	ds_read_b128 v[180:183], v213 offset:5120
	ds_read_b128 v[196:199], v213 offset:6144
	ds_read_b128 v[200:203], v213 offset:7168
	global_load_lds_dwordx4 v192, s[50:51]
	s_add_i32 m0, s9, 0xe000
	s_nop 0
	global_load_lds_dwordx4 v194, s[50:51]
	s_waitcnt vmcnt(8)
	s_waitcnt lgkmcnt(0)
	s_barrier
	v_mfma_f32_16x16x32_bf16 v[124:127], v[128:131], v[160:163], v[124:127]
	v_mfma_f32_16x16x32_bf16 v[124:127], v[132:135], v[164:167], v[124:127]
	v_mfma_f32_16x16x32_bf16 v[120:123], v[140:143], v[164:167], v[120:123]
	v_mfma_f32_16x16x32_bf16 v[120:123], v[136:139], v[160:163], v[120:123]
	v_mfma_f32_16x16x32_bf16 v[104:107], v[136:139], v[168:171], v[104:107]
	v_mfma_f32_16x16x32_bf16 v[104:107], v[140:143], v[172:175], v[104:107]
	v_mfma_f32_16x16x32_bf16 v[108:111], v[132:135], v[172:175], v[108:111]
	v_mfma_f32_16x16x32_bf16 v[108:111], v[128:131], v[168:171], v[108:111]
	v_mfma_f32_16x16x32_bf16 v[92:95], v[128:131], v[176:179], v[92:95]
	v_mfma_f32_16x16x32_bf16 v[92:95], v[132:135], v[180:183], v[92:95]
	v_mfma_f32_16x16x32_bf16 v[88:91], v[140:143], v[180:183], v[88:91]
	v_mfma_f32_16x16x32_bf16 v[88:91], v[136:139], v[176:179], v[88:91]
	v_mfma_f32_16x16x32_bf16 v[72:75], v[136:139], v[196:199], v[72:75]
	v_mfma_f32_16x16x32_bf16 v[72:75], v[140:143], v[200:203], v[72:75]
	v_mfma_f32_16x16x32_bf16 v[76:79], v[132:135], v[200:203], v[76:79]
	v_mfma_f32_16x16x32_bf16 v[76:79], v[128:131], v[196:199], v[76:79]
	v_mfma_f32_16x16x32_bf16 v[116:119], v[144:147], v[160:163], v[116:119]
	v_mfma_f32_16x16x32_bf16 v[116:119], v[148:151], v[164:167], v[116:119]
	v_mfma_f32_16x16x32_bf16 v[112:115], v[156:159], v[164:167], v[112:115]
	v_mfma_f32_16x16x32_bf16 v[112:115], v[152:155], v[160:163], v[112:115]
	v_mfma_f32_16x16x32_bf16 v[96:99], v[152:155], v[168:171], v[96:99]
	v_mfma_f32_16x16x32_bf16 v[96:99], v[156:159], v[172:175], v[96:99]
	v_mfma_f32_16x16x32_bf16 v[100:103], v[148:151], v[172:175], v[100:103]
	v_mfma_f32_16x16x32_bf16 v[100:103], v[144:147], v[168:171], v[100:103]
	v_mfma_f32_16x16x32_bf16 v[84:87], v[144:147], v[176:179], v[84:87]
	v_mfma_f32_16x16x32_bf16 v[84:87], v[148:151], v[180:183], v[84:87]
	v_mfma_f32_16x16x32_bf16 v[80:83], v[156:159], v[180:183], v[80:83]
	v_mfma_f32_16x16x32_bf16 v[80:83], v[152:155], v[176:179], v[80:83]
	v_mfma_f32_16x16x32_bf16 v[64:67], v[152:155], v[196:199], v[64:67]
	v_mfma_f32_16x16x32_bf16 v[64:67], v[156:159], v[200:203], v[64:67]
	v_mfma_f32_16x16x32_bf16 v[68:71], v[148:151], v[200:203], v[68:71]
	v_mfma_f32_16x16x32_bf16 v[68:71], v[144:147], v[196:199], v[68:71]
	s_barrier
	s_add_i32 s45, s75, s60
	s_mov_b32 m0, s45
	ds_read_b128 v[160:163], v213 offset:16384
	ds_read_b128 v[164:167], v213 offset:17408
	ds_read_b128 v[168:171], v213 offset:18432
	ds_read_b128 v[172:175], v213 offset:19456
	ds_read_b128 v[176:179], v213 offset:20480
	ds_read_b128 v[180:183], v213 offset:21504
	ds_read_b128 v[196:199], v213 offset:22528
	ds_read_b128 v[200:203], v213 offset:23552
	global_load_lds_dwordx4 v186, s[52:53]
	s_add_i32 m0, s45, 0x2000
	s_add_u32 s86, s52, 0x400000
	s_addc_u32 s87, s53, 0
	s_add_i32 s45, s76, s60
	global_load_lds_dwordx4 v190, s[52:53]
	s_mov_b32 m0, s45
	s_nop 0
	global_load_lds_dwordx4 v186, s[86:87]
	s_add_i32 m0, s45, 0x2000
	s_nop 0
	global_load_lds_dwordx4 v190, s[86:87]
	s_mov_b32 m0, s9
	s_nop 0
	global_load_lds_dwordx4 v184, s[54:55]
	s_mov_b32 m0, s61
	s_nop 0
	global_load_lds_dwordx4 v188, s[54:55]
	s_waitcnt vmcnt(8)
	s_waitcnt lgkmcnt(0)
	s_barrier
	v_mfma_f32_16x16x32_bf16 v[60:63], v[128:131], v[160:163], v[60:63]
	v_mfma_f32_16x16x32_bf16 v[60:63], v[132:135], v[164:167], v[60:63]
	v_mfma_f32_16x16x32_bf16 v[56:59], v[140:143], v[164:167], v[56:59]
	v_mfma_f32_16x16x32_bf16 v[56:59], v[136:139], v[160:163], v[56:59]
	v_mfma_f32_16x16x32_bf16 v[40:43], v[136:139], v[168:171], v[40:43]
	v_mfma_f32_16x16x32_bf16 v[40:43], v[140:143], v[172:175], v[40:43]
	v_mfma_f32_16x16x32_bf16 v[44:47], v[132:135], v[172:175], v[44:47]
	v_mfma_f32_16x16x32_bf16 v[44:47], v[128:131], v[168:171], v[44:47]
	v_mfma_f32_16x16x32_bf16 v[28:31], v[128:131], v[176:179], v[28:31]
	v_mfma_f32_16x16x32_bf16 v[28:31], v[132:135], v[180:183], v[28:31]
	v_mfma_f32_16x16x32_bf16 v[24:27], v[140:143], v[180:183], v[24:27]
	v_mfma_f32_16x16x32_bf16 v[24:27], v[136:139], v[176:179], v[24:27]
	v_mfma_f32_16x16x32_bf16 v[8:11], v[136:139], v[196:199], v[8:11]
	v_mfma_f32_16x16x32_bf16 v[8:11], v[140:143], v[200:203], v[8:11]
	v_mfma_f32_16x16x32_bf16 v[12:15], v[132:135], v[200:203], v[12:15]
	v_mfma_f32_16x16x32_bf16 v[12:15], v[128:131], v[196:199], v[12:15]
	v_mfma_f32_16x16x32_bf16 v[52:55], v[144:147], v[160:163], v[52:55]
	v_mfma_f32_16x16x32_bf16 v[52:55], v[148:151], v[164:167], v[52:55]
	v_mfma_f32_16x16x32_bf16 v[48:51], v[156:159], v[164:167], v[48:51]
	v_mfma_f32_16x16x32_bf16 v[48:51], v[152:155], v[160:163], v[48:51]
	v_mfma_f32_16x16x32_bf16 v[32:35], v[152:155], v[168:171], v[32:35]
	v_mfma_f32_16x16x32_bf16 v[32:35], v[156:159], v[172:175], v[32:35]
	v_mfma_f32_16x16x32_bf16 v[36:39], v[148:151], v[172:175], v[36:39]
	v_mfma_f32_16x16x32_bf16 v[36:39], v[144:147], v[168:171], v[36:39]
	v_mfma_f32_16x16x32_bf16 v[20:23], v[144:147], v[176:179], v[20:23]
	v_mfma_f32_16x16x32_bf16 v[20:23], v[148:151], v[180:183], v[20:23]
	v_mfma_f32_16x16x32_bf16 v[16:19], v[156:159], v[180:183], v[16:19]
	v_mfma_f32_16x16x32_bf16 v[16:19], v[152:155], v[176:179], v[16:19]
	v_mfma_f32_16x16x32_bf16 v[0:3], v[152:155], v[196:199], v[0:3]
	v_mfma_f32_16x16x32_bf16 v[0:3], v[156:159], v[200:203], v[0:3]
	v_mfma_f32_16x16x32_bf16 v[4:7], v[148:151], v[200:203], v[4:7]
	v_mfma_f32_16x16x32_bf16 v[4:7], v[144:147], v[196:199], v[4:7]
	s_barrier
; #define PG8_STAGE(bufoff, gbase, voff) do { _Pragma("unroll") for (int _i = 0; _i < 2; ++_i) \
;         __builtin_amdgcn_global_load_lds((const unsigned*)((const char*)(gbase) + (voff)[_i]), (PG8_LAS unsigned*)(lds + (bufoff) + ldsw + _i * 8192), 16, 0, 0); } while (0)
; #define PG8_LDA(dst, b, h) do { _Pragma("unroll") for (int m = 0; m < 4; ++m) _Pragma("unroll") for (int k = 0; k < 2; ++k) dst[m][k] = *(const PG8_LAS bf16x8*)(lds + PG8_SA(b, h) + aoff + m * 2048 + k * 1024); } while (0)
; #define PG8_LDB(dst, b, h) do { _Pragma("unroll") for (int n = 0; n < 2; ++n) _Pragma("unroll") for (int k = 0; k < 2; ++k) dst[n][k] = *(const PG8_LAS bf16x8*)(lds + PG8_SB(b, h) + boff + n * 2048 + k * 1024); } while (0)
; #define PG8_MMA(ai, bj, At, Bt) do { __builtin_amdgcn_s_setprio(1); _Pragma("unroll") for (int m = 0; m < 4; ++m) _Pragma("unroll") for (int n = 0; n < 2; ++n) _Pragma("unroll") for (int k = 0; k < 2; ++k) \
;         acc[ai][bj][m][n] = __builtin_amdgcn_mfma_f32_16x16x32_bf16(Bt[n][k], At[m][k], acc[ai][bj][m][n], 0, 0, 0); __builtin_amdgcn_s_setprio(0); } while (0)
; #define PG8_WAIT_V(n) asm volatile("s_waitcnt vmcnt(" #n ")" ::: "memory")
; #define PG8_WAIT_L(n) asm volatile("s_waitcnt lgkmcnt(" #n ")" ::: "memory")
; #define PG8_BAR __builtin_amdgcn_s_barrier()
; #define PG8_SCHED __builtin_amdgcn_sched_barrier(0)
; template <class Epi, class Sched, bool ALIGN_EPI = false, bool SP2 = false>
; __device__ __forceinline__ void gemm_phase(PG8_LAS unsigned char* lds, const Gemm g, const Sched& S, const Epi& E, int wave_s) {
;     ...
;             PG8_LDB(B0, 1, 0); PG8_LDB(B1, 1, 1); PG8_SCHED; PG8_LDA(At, 1, 0); PG8_STAGE(PG8_SA(0, 1), a2 + hstep, voffA);
;             PG8_WAIT_V(8); PG8_WAIT_L(0); PG8_BAR; PG8_MMA(0, 0, At, B0); PG8_MMA(0, 1, At, B1); PG8_BAR; PG8_SCHED;
;             PG8_LDA(At, 1, 1); PG8_STAGE(PG8_SB(1, 0), b3, voffB); PG8_STAGE(PG8_SB(1, 1), b3 + hstep, voffB); PG8_STAGE(PG8_SA(1, 0), a3, voffA);
;             PG8_WAIT_V(8); PG8_WAIT_L(0); PG8_BAR; PG8_MMA(1, 0, At, B0); PG8_MMA(1, 1, At, B1); PG8_BAR; PG8_SCHED;
	s_add_i32 s45, 0, 0x18000
	s_add_i32 s86, 0, 0x1c000
	v_add_u32_e32 v140, s45, v210
	v_add_u32_e32 v156, s86, v210
	ds_read_b128 v[128:131], v140
	ds_read_b128 v[132:135], v140 offset:1024
	ds_read_b128 v[136:139], v140 offset:2048
	ds_read_b128 v[140:143], v140 offset:3072
	ds_read_b128 v[144:147], v156
	ds_read_b128 v[148:151], v156 offset:1024
	ds_read_b128 v[152:155], v156 offset:2048
	ds_read_b128 v[156:159], v156 offset:3072
	s_add_u32 s54, s54, 0x400000
	s_addc_u32 s55, s55, 0
	s_mov_b32 m0, s62
	s_nop 0
	ds_read_b128 v[160:163], v213 offset:32768
	ds_read_b128 v[164:167], v213 offset:33792
	ds_read_b128 v[168:171], v213 offset:34816
	ds_read_b128 v[172:175], v213 offset:35840
	ds_read_b128 v[176:179], v213 offset:36864
	ds_read_b128 v[180:183], v213 offset:37888
	ds_read_b128 v[196:199], v213 offset:38912
	ds_read_b128 v[200:203], v213 offset:39936
	global_load_lds_dwordx4 v184, s[54:55]
	s_mov_b32 m0, s63
	s_nop 0
	global_load_lds_dwordx4 v188, s[54:55]
	s_waitcnt vmcnt(8)
	s_waitcnt lgkmcnt(0)
	s_barrier
	v_mfma_f32_16x16x32_bf16 v[124:127], v[128:131], v[160:163], v[124:127]
	v_mfma_f32_16x16x32_bf16 v[124:127], v[132:135], v[164:167], v[124:127]
	v_mfma_f32_16x16x32_bf16 v[120:123], v[140:143], v[164:167], v[120:123]
	v_mfma_f32_16x16x32_bf16 v[120:123], v[136:139], v[160:163], v[120:123]
	v_mfma_f32_16x16x32_bf16 v[104:107], v[136:139], v[168:171], v[104:107]
	v_mfma_f32_16x16x32_bf16 v[104:107], v[140:143], v[172:175], v[104:107]
	v_mfma_f32_16x16x32_bf16 v[108:111], v[132:135], v[172:175], v[108:111]
	v_mfma_f32_16x16x32_bf16 v[108:111], v[128:131], v[168:171], v[108:111]
	v_mfma_f32_16x16x32_bf16 v[92:95], v[128:131], v[176:179], v[92:95]
	v_mfma_f32_16x16x32_bf16 v[92:95], v[132:135], v[180:183], v[92:95]
	v_mfma_f32_16x16x32_bf16 v[88:91], v[140:143], v[180:183], v[88:91]
	v_mfma_f32_16x16x32_bf16 v[88:91], v[136:139], v[176:179], v[88:91]
	v_mfma_f32_16x16x32_bf16 v[72:75], v[136:139], v[196:199], v[72:75]
	v_mfma_f32_16x16x32_bf16 v[72:75], v[140:143], v[200:203], v[72:75]
	v_mfma_f32_16x16x32_bf16 v[76:79], v[132:135], v[200:203], v[76:79]
	v_mfma_f32_16x16x32_bf16 v[76:79], v[128:131], v[196:199], v[76:79]
	v_mfma_f32_16x16x32_bf16 v[116:119], v[144:147], v[160:163], v[116:119]
	v_mfma_f32_16x16x32_bf16 v[116:119], v[148:151], v[164:167], v[116:119]
	v_mfma_f32_16x16x32_bf16 v[112:115], v[156:159], v[164:167], v[112:115]
	v_mfma_f32_16x16x32_bf16 v[112:115], v[152:155], v[160:163], v[112:115]
	v_mfma_f32_16x16x32_bf16 v[96:99], v[152:155], v[168:171], v[96:99]
	v_mfma_f32_16x16x32_bf16 v[96:99], v[156:159], v[172:175], v[96:99]
	v_mfma_f32_16x16x32_bf16 v[100:103], v[148:151], v[172:175], v[100:103]
	v_mfma_f32_16x16x32_bf16 v[100:103], v[144:147], v[168:171], v[100:103]
	v_mfma_f32_16x16x32_bf16 v[84:87], v[144:147], v[176:179], v[84:87]
	v_mfma_f32_16x16x32_bf16 v[84:87], v[148:151], v[180:183], v[84:87]
	v_mfma_f32_16x16x32_bf16 v[80:83], v[156:159], v[180:183], v[80:83]
	v_mfma_f32_16x16x32_bf16 v[80:83], v[152:155], v[176:179], v[80:83]
	v_mfma_f32_16x16x32_bf16 v[64:67], v[152:155], v[196:199], v[64:67]
	v_mfma_f32_16x16x32_bf16 v[64:67], v[156:159], v[200:203], v[64:67]
	v_mfma_f32_16x16x32_bf16 v[68:71], v[148:151], v[200:203], v[68:71]
	v_mfma_f32_16x16x32_bf16 v[68:71], v[144:147], v[196:199], v[68:71]
	s_barrier
	s_add_i32 s45, s45, s60
	s_mov_b32 m0, s45
	ds_read_b128 v[160:163], v213 offset:49152
	ds_read_b128 v[164:167], v213 offset:50176
	ds_read_b128 v[168:171], v213 offset:51200
	ds_read_b128 v[172:175], v213 offset:52224
	ds_read_b128 v[176:179], v213 offset:53248
	ds_read_b128 v[180:183], v213 offset:54272
	ds_read_b128 v[196:199], v213 offset:55296
	ds_read_b128 v[200:203], v213 offset:56320
	s_add_u32 s94, s52, 0x80
	s_addc_u32 s95, s53, 0
	global_load_lds_dwordx4 v186, s[94:95]
	s_add_i32 m0, s45, 0x2000
	s_add_u32 s52, s52, 0x400080
	s_addc_u32 s53, s53, 0
	s_add_i32 s45, s86, s60
	global_load_lds_dwordx4 v190, s[94:95]
	s_mov_b32 m0, s45
	s_nop 0
	global_load_lds_dwordx4 v186, s[52:53]
	s_add_i32 m0, s45, 0x2000
	s_nop 0
	global_load_lds_dwordx4 v190, s[52:53]
	s_mov_b32 m0, s70
	s_nop 0
	s_add_u32 s96, s54, 0xffc00080
	s_addc_u32 s97, s55, -1
	global_load_lds_dwordx4 v184, s[96:97]
	s_mov_b32 m0, s71
	s_nop 0
	global_load_lds_dwordx4 v188, s[96:97]
	s_waitcnt vmcnt(8)
	s_waitcnt lgkmcnt(0)
	s_barrier
	v_mfma_f32_16x16x32_bf16 v[60:63], v[128:131], v[160:163], v[60:63]
	v_mfma_f32_16x16x32_bf16 v[60:63], v[132:135], v[164:167], v[60:63]
	v_mfma_f32_16x16x32_bf16 v[56:59], v[140:143], v[164:167], v[56:59]
	v_mfma_f32_16x16x32_bf16 v[56:59], v[136:139], v[160:163], v[56:59]
	v_mfma_f32_16x16x32_bf16 v[40:43], v[136:139], v[168:171], v[40:43]
	v_mfma_f32_16x16x32_bf16 v[40:43], v[140:143], v[172:175], v[40:43]
	v_mfma_f32_16x16x32_bf16 v[44:47], v[132:135], v[172:175], v[44:47]
	v_mfma_f32_16x16x32_bf16 v[44:47], v[128:131], v[168:171], v[44:47]
	v_mfma_f32_16x16x32_bf16 v[28:31], v[128:131], v[176:179], v[28:31]
	v_mfma_f32_16x16x32_bf16 v[28:31], v[132:135], v[180:183], v[28:31]
	v_mfma_f32_16x16x32_bf16 v[24:27], v[140:143], v[180:183], v[24:27]
	v_mfma_f32_16x16x32_bf16 v[24:27], v[136:139], v[176:179], v[24:27]
	v_mfma_f32_16x16x32_bf16 v[8:11], v[136:139], v[196:199], v[8:11]
	v_mfma_f32_16x16x32_bf16 v[8:11], v[140:143], v[200:203], v[8:11]
	v_mfma_f32_16x16x32_bf16 v[12:15], v[132:135], v[200:203], v[12:15]
	v_mfma_f32_16x16x32_bf16 v[12:15], v[128:131], v[196:199], v[12:15]
	v_mfma_f32_16x16x32_bf16 v[52:55], v[144:147], v[160:163], v[52:55]
	v_mfma_f32_16x16x32_bf16 v[52:55], v[148:151], v[164:167], v[52:55]
	v_mfma_f32_16x16x32_bf16 v[48:51], v[156:159], v[164:167], v[48:51]
	v_mfma_f32_16x16x32_bf16 v[48:51], v[152:155], v[160:163], v[48:51]
	v_mfma_f32_16x16x32_bf16 v[32:35], v[152:155], v[168:171], v[32:35]
	v_mfma_f32_16x16x32_bf16 v[32:35], v[156:159], v[172:175], v[32:35]
	v_mfma_f32_16x16x32_bf16 v[36:39], v[148:151], v[172:175], v[36:39]
	v_mfma_f32_16x16x32_bf16 v[36:39], v[144:147], v[168:171], v[36:39]
	v_mfma_f32_16x16x32_bf16 v[20:23], v[144:147], v[176:179], v[20:23]
	v_mfma_f32_16x16x32_bf16 v[20:23], v[148:151], v[180:183], v[20:23]
	v_mfma_f32_16x16x32_bf16 v[16:19], v[156:159], v[180:183], v[16:19]
	v_mfma_f32_16x16x32_bf16 v[16:19], v[152:155], v[176:179], v[16:19]
	v_mfma_f32_16x16x32_bf16 v[0:3], v[152:155], v[196:199], v[0:3]
	v_mfma_f32_16x16x32_bf16 v[0:3], v[156:159], v[200:203], v[0:3]
	v_mfma_f32_16x16x32_bf16 v[4:7], v[148:151], v[200:203], v[4:7]
	v_mfma_f32_16x16x32_bf16 v[4:7], v[144:147], v[196:199], v[4:7]
	s_barrier
	s_add_i32 s45, s43, 2
	s_add_u32 s50, s50, 0x100
	s_addc_u32 s51, s51, 0
	s_add_u32 s7, s7, 0x100
	s_addc_u32 s41, s41, 0
	s_cmp_ge_i32 s43, s85
	s_mov_b32 s43, s45
	s_cbranch_scc0 .LBB0_1410
	s_and_b64 vcc, exec, s[20:21]
	s_cbranch_vccz .LBB0_1413
	s_barrier
